# merge phase: the 64 serial gate loads of each rescale pass issued in two batches of 32 (one wait each)
# baseline (speedup 1.0000x reference)
; __device__ __forceinline__ float lo_bf(unsigned u) { return __uint_as_float(u << 16); }
; __device__ __forceinline__ float hi_bf(unsigned u) { return __uint_as_float(u & 0xffff0000u); }
; __device__ __forceinline__ TileIdx tile_idx() { TileIdx t; t.tid = fresh_tid(); t.wid = t.tid >> 6; t.lane = t.tid & 63; t.wr = t.wid >> 2; t.wc = t.wid & 3; t.fr = t.lane & 15; t.fq = t.lane >> 4; return t; }
; __device__ __forceinline__ void phase_merge(const Ctx& a, LAS unsigned char* lds) {
;     ...
;         for (int seg = 0; seg < 3; ++seg) {
;             gemm_kloop(acc, br + seg * 512, BR, W + seg * 512, BR, pm * 256, pn * 256, 512 / 64, lds);
;             __syncthreads();
;             TileIdx t = tile_idx();
; #pragma unroll
;             for (int ai = 0; ai < 2; ++ai)
; #pragma unroll
;                 for (int m = 0; m < 4; ++m) {
;                     int row = pm * 256 + ai * 128 + t.wr * 64 + m * 16 + t.fr;
; #pragma unroll
;                     for (int bj = 0; bj < 2; ++bj)
; #pragma unroll
;                         for (int n = 0; n < 2; ++n) {
;                             int col = pn * 256 + bj * 128 + t.wc * 32 + n * 16 + t.fq * 4;
;                             const bf16_t* gp = g + (size_t)row * NG + col;
;                             u32x2 gc = *(const u32x2*)(gp + seg * DM);
;                             float c0 = lo_bf(gc[0]), c1 = hi_bf(gc[0]), c2 = lo_bf(gc[1]), c3 = hi_bf(gc[1]);
;                             if (seg < 2) {
;                                 u32x2 gn = *(const u32x2*)(gp + (seg + 1) * DM);
;                                 c0 = c0 / fmaxf(lo_bf(gn[0]), 1e-30f); c1 = c1 / fmaxf(hi_bf(gn[0]), 1e-30f);
;                                 c2 = c2 / fmaxf(lo_bf(gn[1]), 1e-30f); c3 = c3 / fmaxf(hi_bf(gn[1]), 1e-30f);
;                                 acc[ai][bj][m][n][0] *= c0; acc[ai][bj][m][n][1] *= c1; acc[ai][bj][m][n][2] *= c2; acc[ai][bj][m][n][3] *= c3;
.LBB0_558:
	s_or_b64 exec, exec, s[12:13]
	s_waitcnt vmcnt(0)
	s_barrier
	v_mov_b32 v1, v179
	s_lshl_b32 s8, s9, 11
	v_ashrrev_i32_e32 v2, 2, v1
	v_and_b32_e32 v2, 0xffffffc0, v2
	v_and_or_b32 v3, v1, 15, s68
	v_add_u32_e32 v136, v3, v2
	v_lshrrev_b32_e32 v2, 1, v1
	v_lshrrev_b32_e32 v1, 2, v1
	s_add_u32 s52, s70, s8
	v_and_b32_e32 v2, 0x60, v2
	v_and_b32_e32 v1, 12, v1
	s_addc_u32 s53, s71, 0
	v_or3_b32 v134, v1, v2, s69
	v_mov_b64_e32 v[2:3], s[52:53]
	v_mad_i64_i32 v[2:3], s[12:13], v136, s84, v[2:3]
	v_ashrrev_i32_e32 v135, 31, v134
	v_lshl_add_u64 v[138:139], v[134:135], 1, v[2:3]
	v_mov_b32_e32 v150, v138
	v_mov_b32_e32 v151, v139
	global_load_dwordx2 v[154:155], v[150:151], off
	global_load_dwordx2 v[156:157], v[150:151], off offset:2048
	global_load_dwordx2 v[158:159], v[150:151], off offset:32
	global_load_dwordx2 v[160:161], v[150:151], off offset:2080
	global_load_dwordx2 v[162:163], v[150:151], off offset:256
	global_load_dwordx2 v[164:165], v[150:151], off offset:2304
	global_load_dwordx2 v[166:167], v[150:151], off offset:288
	global_load_dwordx2 v[168:169], v[150:151], off offset:2336
	v_mov_b32_e32 v250, 0x18000
	v_mov_b32_e32 v251, 0
	v_lshl_add_u64 v[152:153], v[250:251], 0, v[150:151]
	global_load_dwordx2 v[170:171], v[152:153], off
	global_load_dwordx2 v[172:173], v[152:153], off offset:2048
	global_load_dwordx2 v[174:175], v[152:153], off offset:32
	global_load_dwordx2 v[176:177], v[152:153], off offset:2080
	global_load_dwordx2 v[184:185], v[152:153], off offset:256
	global_load_dwordx2 v[186:187], v[152:153], off offset:2304
	global_load_dwordx2 v[188:189], v[152:153], off offset:288
	global_load_dwordx2 v[190:191], v[152:153], off offset:2336
	v_mov_b32_e32 v250, 0x30000
	v_mov_b32_e32 v251, 0
	v_lshl_add_u64 v[152:153], v[250:251], 0, v[150:151]
	global_load_dwordx2 v[192:193], v[152:153], off
	global_load_dwordx2 v[200:201], v[152:153], off offset:2048
	global_load_dwordx2 v[202:203], v[152:153], off offset:32
	global_load_dwordx2 v[204:205], v[152:153], off offset:2080
	global_load_dwordx2 v[206:207], v[152:153], off offset:256
	global_load_dwordx2 v[208:209], v[152:153], off offset:2304
	global_load_dwordx2 v[210:211], v[152:153], off offset:288
	global_load_dwordx2 v[212:213], v[152:153], off offset:2336
	v_mov_b32_e32 v250, 0x48000
	v_mov_b32_e32 v251, 0
	v_lshl_add_u64 v[152:153], v[250:251], 0, v[150:151]
	global_load_dwordx2 v[214:215], v[152:153], off
	global_load_dwordx2 v[216:217], v[152:153], off offset:2048
	global_load_dwordx2 v[218:219], v[152:153], off offset:32
	global_load_dwordx2 v[220:221], v[152:153], off offset:2080
	global_load_dwordx2 v[222:223], v[152:153], off offset:256
	global_load_dwordx2 v[224:225], v[152:153], off offset:2304
	global_load_dwordx2 v[226:227], v[152:153], off offset:288
	global_load_dwordx2 v[228:229], v[152:153], off offset:2336
	s_waitcnt vmcnt(0)
	v_mov_b32_e32 v2, v154
	v_mov_b32_e32 v3, v155
	s_cmp_lg_u32 s9, 2
	s_cselect_b64 s[12:13], -1, 0
	s_cmp_eq_u32 s9, 2
	s_mov_b64 s[36:37], -1
	s_waitcnt vmcnt(0)
	v_lshlrev_b32_e32 v146, 16, v2
	v_and_b32_e32 v147, 0xffff0000, v2
	v_lshlrev_b32_e32 v142, 16, v3
	v_and_b32_e32 v143, 0xffff0000, v3
	s_cbranch_scc1 .LBB0_560
	v_mov_b32_e32 v2, v156
	v_mov_b32_e32 v3, v157
	s_waitcnt vmcnt(0)
	v_lshlrev_b32_e32 v1, 16, v2
	v_and_b32_e32 v2, 0xffff0000, v2
	v_max_f32_e32 v2, v2, v2
	v_lshlrev_b32_e32 v4, 16, v3
	v_and_b32_e32 v3, 0xffff0000, v3
	v_max_f32_e32 v2, 0xda24260, v2
	v_max_f32_e32 v3, v3, v3
	v_max_f32_e32 v5, 0xda24260, v3
	v_div_scale_f32 v3, s[36:37], v2, v2, v147
	v_rcp_f32_e32 v137, v3
	v_max_f32_e32 v1, v1, v1
	v_max_f32_e32 v1, 0xda24260, v1
	v_max_f32_e32 v4, v4, v4
	v_fma_f32 v140, -v3, v137, 1.0
	v_fmac_f32_e32 v137, v140, v137
	v_div_scale_f32 v140, vcc, v147, v2, v147
	v_mul_f32_e32 v141, v140, v137
	v_fma_f32 v144, -v3, v141, v140
	v_fmac_f32_e32 v141, v144, v137
	v_fma_f32 v3, -v3, v141, v140
	v_div_fmas_f32 v3, v3, v137, v141
	v_div_fixup_f32 v3, v3, v2, v147
	v_div_scale_f32 v2, s[36:37], v1, v1, v146
	v_rcp_f32_e32 v137, v2
	v_max_f32_e32 v4, 0xda24260, v4
	v_fma_f32 v140, -v2, v137, 1.0
	v_fmac_f32_e32 v137, v140, v137
	v_div_scale_f32 v140, vcc, v146, v1, v146
	v_mul_f32_e32 v141, v140, v137
	v_fma_f32 v144, -v2, v141, v140
	v_fmac_f32_e32 v141, v144, v137
	v_fma_f32 v2, -v2, v141, v140
	v_div_fmas_f32 v2, v2, v137, v141
	v_div_fixup_f32 v2, v2, v1, v146
	v_div_scale_f32 v1, s[36:37], v5, v5, v143
	v_rcp_f32_e32 v137, v1
	v_pk_mul_f32 v[2:3], v[10:11], v[2:3]
	v_fma_f32 v140, -v1, v137, 1.0
	v_fmac_f32_e32 v137, v140, v137
	v_div_scale_f32 v140, vcc, v143, v5, v143
	v_mul_f32_e32 v141, v140, v137
	v_fma_f32 v144, -v1, v141, v140
	v_fmac_f32_e32 v141, v144, v137
	v_fma_f32 v1, -v1, v141, v140
	v_div_fmas_f32 v1, v1, v137, v141
	v_div_fixup_f32 v5, v1, v5, v143
	v_div_scale_f32 v1, s[36:37], v4, v4, v142
	v_rcp_f32_e32 v137, v1
	s_mov_b64 s[36:37], 0
	v_fma_f32 v140, -v1, v137, 1.0
	v_fmac_f32_e32 v137, v140, v137
	v_div_scale_f32 v140, vcc, v142, v4, v142
	v_mul_f32_e32 v141, v140, v137
	v_fma_f32 v144, -v1, v141, v140
	v_fmac_f32_e32 v141, v144, v137
	v_fma_f32 v1, -v1, v141, v140
	v_div_fmas_f32 v1, v1, v137, v141
	v_div_fixup_f32 v4, v1, v4, v142
	v_pk_mul_f32 v[4:5], v[12:13], v[4:5]

; __device__ __forceinline__ float lo_bf(unsigned u) { return __uint_as_float(u << 16); }
; __device__ __forceinline__ float hi_bf(unsigned u) { return __uint_as_float(u & 0xffff0000u); }
; __device__ __forceinline__ void phase_merge(const Ctx& a, LAS unsigned char* lds) {
;     ...
;                             const bf16_t* gp = g + (size_t)row * NG + col;
;                             u32x2 gc = *(const u32x2*)(gp + seg * DM);
;                             float c0 = lo_bf(gc[0]), c1 = hi_bf(gc[0]), c2 = lo_bf(gc[1]), c3 = hi_bf(gc[1]);
;                             if (seg < 2) {
;                                 u32x2 gn = *(const u32x2*)(gp + (seg + 1) * DM);
;                                 c0 = c0 / fmaxf(lo_bf(gn[0]), 1e-30f); c1 = c1 / fmaxf(hi_bf(gn[0]), 1e-30f);
;                                 c2 = c2 / fmaxf(lo_bf(gn[1]), 1e-30f); c3 = c3 / fmaxf(hi_bf(gn[1]), 1e-30f);
;                                 acc[ai][bj][m][n][0] *= c0; acc[ai][bj][m][n][1] *= c1; acc[ai][bj][m][n][2] *= c2; acc[ai][bj][m][n][3] *= c3;
.LBB0_562:
	v_mov_b32_e32 v10, v158
	v_mov_b32_e32 v11, v159
	v_cndmask_b32_e64 v1, 0, 1, s[12:13]
	v_cmp_ne_u32_e64 s[36:37], 1, v1
	s_andn2_b64 vcc, exec, s[12:13]
	s_mov_b64 s[12:13], -1
	s_waitcnt vmcnt(0)
	v_lshlrev_b32_e32 v146, 16, v10
	v_and_b32_e32 v147, 0xffff0000, v10
	v_lshlrev_b32_e32 v142, 16, v11
	v_and_b32_e32 v143, 0xffff0000, v11
	s_cbranch_vccnz .LBB0_564
	v_mov_b32_e32 v10, v160
	v_mov_b32_e32 v11, v161
	s_waitcnt vmcnt(0)
	v_lshlrev_b32_e32 v1, 16, v10
	v_and_b32_e32 v10, 0xffff0000, v10
	v_max_f32_e32 v10, v10, v10
	v_lshlrev_b32_e32 v12, 16, v11
	v_and_b32_e32 v11, 0xffff0000, v11
	v_max_f32_e32 v10, 0xda24260, v10
	v_max_f32_e32 v11, v11, v11
	v_max_f32_e32 v13, 0xda24260, v11
	v_div_scale_f32 v11, s[12:13], v10, v10, v147
	v_rcp_f32_e32 v137, v11
	v_max_f32_e32 v1, v1, v1
	v_max_f32_e32 v1, 0xda24260, v1
	v_max_f32_e32 v12, v12, v12
	v_fma_f32 v144, -v11, v137, 1.0
	v_fmac_f32_e32 v137, v144, v137
	v_div_scale_f32 v144, vcc, v147, v10, v147
	v_mul_f32_e32 v148, v144, v137
	v_fma_f32 v149, -v11, v148, v144
	v_fmac_f32_e32 v148, v149, v137
	v_fma_f32 v11, -v11, v148, v144
	v_div_fmas_f32 v11, v11, v137, v148
	v_div_fixup_f32 v11, v11, v10, v147
	v_div_scale_f32 v10, s[12:13], v1, v1, v146
	v_rcp_f32_e32 v137, v10
	v_max_f32_e32 v12, 0xda24260, v12
	v_fma_f32 v144, -v10, v137, 1.0
	v_fmac_f32_e32 v137, v144, v137
	v_div_scale_f32 v144, vcc, v146, v1, v146
	v_mul_f32_e32 v148, v144, v137
	v_fma_f32 v149, -v10, v148, v144
	v_fmac_f32_e32 v148, v149, v137
	v_fma_f32 v10, -v10, v148, v144
	v_div_fmas_f32 v10, v10, v137, v148
	v_div_fixup_f32 v10, v10, v1, v146
	v_div_scale_f32 v1, s[12:13], v13, v13, v143
	v_rcp_f32_e32 v137, v1
	v_pk_mul_f32 v[10:11], v[18:19], v[10:11]
	v_fma_f32 v144, -v1, v137, 1.0
	v_fmac_f32_e32 v137, v144, v137
	v_div_scale_f32 v144, vcc, v143, v13, v143
	v_mul_f32_e32 v148, v144, v137
	v_fma_f32 v149, -v1, v148, v144
	v_fmac_f32_e32 v148, v149, v137
	v_fma_f32 v1, -v1, v148, v144
	v_div_fmas_f32 v1, v1, v137, v148
	v_div_fixup_f32 v13, v1, v13, v143
	v_div_scale_f32 v1, s[12:13], v12, v12, v142
	v_rcp_f32_e32 v137, v1
	s_mov_b64 s[12:13], 0
	v_fma_f32 v144, -v1, v137, 1.0
	v_fmac_f32_e32 v137, v144, v137
	v_div_scale_f32 v144, vcc, v142, v12, v142
	v_mul_f32_e32 v148, v144, v137
	v_fma_f32 v149, -v1, v148, v144
	v_fmac_f32_e32 v148, v149, v137
	v_fma_f32 v1, -v1, v148, v144
	v_div_fmas_f32 v1, v1, v137, v148
	v_div_fixup_f32 v12, v1, v12, v142
	v_pk_mul_f32 v[12:13], v[20:21], v[12:13]

; __device__ __forceinline__ float lo_bf(unsigned u) { return __uint_as_float(u << 16); }
; __device__ __forceinline__ float hi_bf(unsigned u) { return __uint_as_float(u & 0xffff0000u); }
; __device__ __forceinline__ void phase_merge(const Ctx& a, LAS unsigned char* lds) {
;     ...
;                             const bf16_t* gp = g + (size_t)row * NG + col;
;                             u32x2 gc = *(const u32x2*)(gp + seg * DM);
;                             float c0 = lo_bf(gc[0]), c1 = hi_bf(gc[0]), c2 = lo_bf(gc[1]), c3 = hi_bf(gc[1]);
;                             if (seg < 2) {
;                                 u32x2 gn = *(const u32x2*)(gp + (seg + 1) * DM);
;                                 c0 = c0 / fmaxf(lo_bf(gn[0]), 1e-30f); c1 = c1 / fmaxf(hi_bf(gn[0]), 1e-30f);
;                                 c2 = c2 / fmaxf(lo_bf(gn[1]), 1e-30f); c3 = c3 / fmaxf(hi_bf(gn[1]), 1e-30f);
;                                 acc[ai][bj][m][n][0] *= c0; acc[ai][bj][m][n][1] *= c1; acc[ai][bj][m][n][2] *= c2; acc[ai][bj][m][n][3] *= c3;
.LBB0_566:
	v_mov_b32_e32 v18, v162
	v_mov_b32_e32 v19, v163
	s_and_b64 vcc, exec, s[36:37]
	s_mov_b64 s[12:13], -1
	s_waitcnt vmcnt(0)
	v_lshlrev_b32_e32 v146, 16, v18
	v_and_b32_e32 v147, 0xffff0000, v18
	v_lshlrev_b32_e32 v142, 16, v19
	v_and_b32_e32 v143, 0xffff0000, v19
	s_cbranch_vccnz .LBB0_568
	v_mov_b32_e32 v18, v164
	v_mov_b32_e32 v19, v165
	s_waitcnt vmcnt(0)
	v_lshlrev_b32_e32 v1, 16, v18
	v_and_b32_e32 v18, 0xffff0000, v18
	v_max_f32_e32 v18, v18, v18
	v_lshlrev_b32_e32 v20, 16, v19
	v_and_b32_e32 v19, 0xffff0000, v19
	v_max_f32_e32 v18, 0xda24260, v18
	v_max_f32_e32 v19, v19, v19
	v_max_f32_e32 v21, 0xda24260, v19
	v_div_scale_f32 v19, s[12:13], v18, v18, v147
	v_rcp_f32_e32 v137, v19
	v_max_f32_e32 v1, v1, v1
	v_max_f32_e32 v1, 0xda24260, v1
	v_max_f32_e32 v20, v20, v20
	v_fma_f32 v144, -v19, v137, 1.0
	v_fmac_f32_e32 v137, v144, v137
	v_div_scale_f32 v144, vcc, v147, v18, v147
	v_mul_f32_e32 v148, v144, v137
	v_fma_f32 v149, -v19, v148, v144
	v_fmac_f32_e32 v148, v149, v137
	v_fma_f32 v19, -v19, v148, v144
	v_div_fmas_f32 v19, v19, v137, v148
	v_div_fixup_f32 v19, v19, v18, v147
	v_div_scale_f32 v18, s[12:13], v1, v1, v146
	v_rcp_f32_e32 v137, v18
	v_max_f32_e32 v20, 0xda24260, v20
	v_fma_f32 v144, -v18, v137, 1.0
	v_fmac_f32_e32 v137, v144, v137
	v_div_scale_f32 v144, vcc, v146, v1, v146
	v_mul_f32_e32 v148, v144, v137
	v_fma_f32 v149, -v18, v148, v144
	v_fmac_f32_e32 v148, v149, v137
	v_fma_f32 v18, -v18, v148, v144
	v_div_fmas_f32 v18, v18, v137, v148
	v_div_fixup_f32 v18, v18, v1, v146
	v_div_scale_f32 v1, s[12:13], v21, v21, v143
	v_rcp_f32_e32 v137, v1
	v_pk_mul_f32 v[18:19], v[26:27], v[18:19]
	v_fma_f32 v144, -v1, v137, 1.0
	v_fmac_f32_e32 v137, v144, v137
	v_div_scale_f32 v144, vcc, v143, v21, v143
	v_mul_f32_e32 v148, v144, v137
	v_fma_f32 v149, -v1, v148, v144
	v_fmac_f32_e32 v148, v149, v137
	v_fma_f32 v1, -v1, v148, v144
	v_div_fmas_f32 v1, v1, v137, v148
	v_div_fixup_f32 v21, v1, v21, v143
	v_div_scale_f32 v1, s[12:13], v20, v20, v142
	v_rcp_f32_e32 v137, v1
	s_mov_b64 s[12:13], 0
	v_fma_f32 v144, -v1, v137, 1.0
	v_fmac_f32_e32 v137, v144, v137
	v_div_scale_f32 v144, vcc, v142, v20, v142
	v_mul_f32_e32 v148, v144, v137
	v_fma_f32 v149, -v1, v148, v144
	v_fmac_f32_e32 v148, v149, v137
	v_fma_f32 v1, -v1, v148, v144
	v_div_fmas_f32 v1, v1, v137, v148
	v_div_fixup_f32 v20, v1, v20, v142
	v_pk_mul_f32 v[20:21], v[28:29], v[20:21]

; __device__ __forceinline__ float lo_bf(unsigned u) { return __uint_as_float(u << 16); }
; __device__ __forceinline__ float hi_bf(unsigned u) { return __uint_as_float(u & 0xffff0000u); }
; __device__ __forceinline__ void phase_merge(const Ctx& a, LAS unsigned char* lds) {
;     ...
;                             const bf16_t* gp = g + (size_t)row * NG + col;
;                             u32x2 gc = *(const u32x2*)(gp + seg * DM);
;                             float c0 = lo_bf(gc[0]), c1 = hi_bf(gc[0]), c2 = lo_bf(gc[1]), c3 = hi_bf(gc[1]);
;                             if (seg < 2) {
;                                 u32x2 gn = *(const u32x2*)(gp + (seg + 1) * DM);
;                                 c0 = c0 / fmaxf(lo_bf(gn[0]), 1e-30f); c1 = c1 / fmaxf(hi_bf(gn[0]), 1e-30f);
;                                 c2 = c2 / fmaxf(lo_bf(gn[1]), 1e-30f); c3 = c3 / fmaxf(hi_bf(gn[1]), 1e-30f);
;                                 acc[ai][bj][m][n][0] *= c0; acc[ai][bj][m][n][1] *= c1; acc[ai][bj][m][n][2] *= c2; acc[ai][bj][m][n][3] *= c3;
.LBB0_570:
	v_mov_b32_e32 v26, v166
	v_mov_b32_e32 v27, v167
	s_and_b64 vcc, exec, s[36:37]
	s_mov_b64 s[12:13], -1
	s_waitcnt vmcnt(0)
	v_lshlrev_b32_e32 v146, 16, v26
	v_and_b32_e32 v147, 0xffff0000, v26
	v_lshlrev_b32_e32 v142, 16, v27
	v_and_b32_e32 v143, 0xffff0000, v27
	s_cbranch_vccnz .LBB0_572
	v_mov_b32_e32 v26, v168
	v_mov_b32_e32 v27, v169
	s_waitcnt vmcnt(0)
	v_lshlrev_b32_e32 v1, 16, v26
	v_and_b32_e32 v26, 0xffff0000, v26
	v_max_f32_e32 v26, v26, v26
	v_lshlrev_b32_e32 v28, 16, v27
	v_and_b32_e32 v27, 0xffff0000, v27
	v_max_f32_e32 v26, 0xda24260, v26
	v_max_f32_e32 v27, v27, v27
	v_max_f32_e32 v29, 0xda24260, v27
	v_div_scale_f32 v27, s[12:13], v26, v26, v147
	v_rcp_f32_e32 v137, v27
	v_max_f32_e32 v1, v1, v1
	v_max_f32_e32 v1, 0xda24260, v1
	v_max_f32_e32 v28, v28, v28
	v_fma_f32 v138, -v27, v137, 1.0
	v_fmac_f32_e32 v137, v138, v137
	v_div_scale_f32 v138, vcc, v147, v26, v147
	v_mul_f32_e32 v139, v138, v137
	v_fma_f32 v144, -v27, v139, v138
	v_fmac_f32_e32 v139, v144, v137
	v_fma_f32 v27, -v27, v139, v138
	v_div_fmas_f32 v27, v27, v137, v139
	v_div_fixup_f32 v27, v27, v26, v147
	v_div_scale_f32 v26, s[12:13], v1, v1, v146
	v_rcp_f32_e32 v137, v26
	v_max_f32_e32 v28, 0xda24260, v28
	v_fma_f32 v138, -v26, v137, 1.0
	v_fmac_f32_e32 v137, v138, v137
	v_div_scale_f32 v138, vcc, v146, v1, v146
	v_mul_f32_e32 v139, v138, v137
	v_fma_f32 v144, -v26, v139, v138
	v_fmac_f32_e32 v139, v144, v137
	v_fma_f32 v26, -v26, v139, v138
	v_div_fmas_f32 v26, v26, v137, v139
	v_div_fixup_f32 v26, v26, v1, v146
	v_div_scale_f32 v1, s[12:13], v29, v29, v143
	v_rcp_f32_e32 v137, v1
	v_pk_mul_f32 v[26:27], v[34:35], v[26:27]
	v_fma_f32 v138, -v1, v137, 1.0
	v_fmac_f32_e32 v137, v138, v137
	v_div_scale_f32 v138, vcc, v143, v29, v143
	v_mul_f32_e32 v139, v138, v137
	v_fma_f32 v144, -v1, v139, v138
	v_fmac_f32_e32 v139, v144, v137
	v_fma_f32 v1, -v1, v139, v138
	v_div_fmas_f32 v1, v1, v137, v139
	v_div_fixup_f32 v29, v1, v29, v143
	v_div_scale_f32 v1, s[12:13], v28, v28, v142
	v_rcp_f32_e32 v137, v1
	s_mov_b64 s[12:13], 0
	v_fma_f32 v138, -v1, v137, 1.0
	v_fmac_f32_e32 v137, v138, v137
	v_div_scale_f32 v138, vcc, v142, v28, v142
	v_mul_f32_e32 v139, v138, v137
	v_fma_f32 v144, -v1, v139, v138
	v_fmac_f32_e32 v139, v144, v137
	v_fma_f32 v1, -v1, v139, v138
	v_div_fmas_f32 v1, v1, v137, v139
	v_div_fixup_f32 v28, v1, v28, v142
	v_pk_mul_f32 v[28:29], v[36:37], v[28:29]

; __device__ __forceinline__ float lo_bf(unsigned u) { return __uint_as_float(u << 16); }
; __device__ __forceinline__ float hi_bf(unsigned u) { return __uint_as_float(u & 0xffff0000u); }
; __device__ __forceinline__ void phase_merge(const Ctx& a, LAS unsigned char* lds) {
;     ...
;                             const bf16_t* gp = g + (size_t)row * NG + col;
;                             u32x2 gc = *(const u32x2*)(gp + seg * DM);
;                             float c0 = lo_bf(gc[0]), c1 = hi_bf(gc[0]), c2 = lo_bf(gc[1]), c3 = hi_bf(gc[1]);
;                             if (seg < 2) {
;                                 u32x2 gn = *(const u32x2*)(gp + (seg + 1) * DM);
;                                 c0 = c0 / fmaxf(lo_bf(gn[0]), 1e-30f); c1 = c1 / fmaxf(hi_bf(gn[0]), 1e-30f);
;                                 c2 = c2 / fmaxf(lo_bf(gn[1]), 1e-30f); c3 = c3 / fmaxf(hi_bf(gn[1]), 1e-30f);
;                                 acc[ai][bj][m][n][0] *= c0; acc[ai][bj][m][n][1] *= c1; acc[ai][bj][m][n][2] *= c2; acc[ai][bj][m][n][3] *= c3;
.LBB0_574:
	v_or_b32_e32 v140, 16, v136
	v_mov_b64_e32 v[34:35], s[52:53]
	v_mad_i64_i32 v[34:35], s[12:13], v140, s84, v[34:35]
	v_lshl_add_u64 v[138:139], v[134:135], 1, v[34:35]
	v_mov_b32_e32 v34, v170
	v_mov_b32_e32 v35, v171
	s_and_b64 vcc, exec, s[36:37]
	s_mov_b64 s[12:13], -1
	s_waitcnt vmcnt(0)
	v_lshlrev_b32_e32 v146, 16, v34
	v_and_b32_e32 v147, 0xffff0000, v34
	v_lshlrev_b32_e32 v142, 16, v35
	v_and_b32_e32 v143, 0xffff0000, v35
	s_cbranch_vccnz .LBB0_576
	v_mov_b32_e32 v34, v172
	v_mov_b32_e32 v35, v173
	s_waitcnt vmcnt(0)
	v_lshlrev_b32_e32 v1, 16, v34
	v_and_b32_e32 v34, 0xffff0000, v34
	v_max_f32_e32 v34, v34, v34
	v_lshlrev_b32_e32 v36, 16, v35
	v_and_b32_e32 v35, 0xffff0000, v35
	v_max_f32_e32 v34, 0xda24260, v34
	v_max_f32_e32 v35, v35, v35
	v_max_f32_e32 v37, 0xda24260, v35
	v_div_scale_f32 v35, s[12:13], v34, v34, v147
	v_rcp_f32_e32 v137, v35
	v_max_f32_e32 v1, v1, v1
	v_max_f32_e32 v1, 0xda24260, v1
	v_max_f32_e32 v36, v36, v36
	v_fma_f32 v141, -v35, v137, 1.0
	v_fmac_f32_e32 v137, v141, v137
	v_div_scale_f32 v141, vcc, v147, v34, v147
	v_mul_f32_e32 v144, v141, v137
	v_fma_f32 v148, -v35, v144, v141
	v_fmac_f32_e32 v144, v148, v137
	v_fma_f32 v35, -v35, v144, v141
	v_div_fmas_f32 v35, v35, v137, v144
	v_div_fixup_f32 v35, v35, v34, v147
	v_div_scale_f32 v34, s[12:13], v1, v1, v146
	v_rcp_f32_e32 v137, v34
	v_max_f32_e32 v36, 0xda24260, v36
	v_fma_f32 v141, -v34, v137, 1.0
	v_fmac_f32_e32 v137, v141, v137
	v_div_scale_f32 v141, vcc, v146, v1, v146
	v_mul_f32_e32 v144, v141, v137
	v_fma_f32 v148, -v34, v144, v141
	v_fmac_f32_e32 v144, v148, v137
	v_fma_f32 v34, -v34, v144, v141
	v_div_fmas_f32 v34, v34, v137, v144
	v_div_fixup_f32 v34, v34, v1, v146
	v_div_scale_f32 v1, s[12:13], v37, v37, v143
	v_rcp_f32_e32 v137, v1
	v_pk_mul_f32 v[34:35], v[42:43], v[34:35]
	v_fma_f32 v141, -v1, v137, 1.0
	v_fmac_f32_e32 v137, v141, v137
	v_div_scale_f32 v141, vcc, v143, v37, v143
	v_mul_f32_e32 v144, v141, v137
	v_fma_f32 v148, -v1, v144, v141
	v_fmac_f32_e32 v144, v148, v137
	v_fma_f32 v1, -v1, v144, v141
	v_div_fmas_f32 v1, v1, v137, v144
	v_div_fixup_f32 v37, v1, v37, v143
	v_div_scale_f32 v1, s[12:13], v36, v36, v142
	v_rcp_f32_e32 v137, v1
	s_mov_b64 s[12:13], 0
	v_fma_f32 v141, -v1, v137, 1.0
	v_fmac_f32_e32 v137, v141, v137
	v_div_scale_f32 v141, vcc, v142, v36, v142
	v_mul_f32_e32 v144, v141, v137
	v_fma_f32 v148, -v1, v144, v141
	v_fmac_f32_e32 v144, v148, v137
	v_fma_f32 v1, -v1, v144, v141
	v_div_fmas_f32 v1, v1, v137, v144
	v_div_fixup_f32 v36, v1, v36, v142
	v_pk_mul_f32 v[36:37], v[44:45], v[36:37]

; __device__ __forceinline__ float lo_bf(unsigned u) { return __uint_as_float(u << 16); }
; __device__ __forceinline__ float hi_bf(unsigned u) { return __uint_as_float(u & 0xffff0000u); }
; __device__ __forceinline__ void phase_merge(const Ctx& a, LAS unsigned char* lds) {
;     ...
;                             const bf16_t* gp = g + (size_t)row * NG + col;
;                             u32x2 gc = *(const u32x2*)(gp + seg * DM);
;                             float c0 = lo_bf(gc[0]), c1 = hi_bf(gc[0]), c2 = lo_bf(gc[1]), c3 = hi_bf(gc[1]);
;                             if (seg < 2) {
;                                 u32x2 gn = *(const u32x2*)(gp + (seg + 1) * DM);
;                                 c0 = c0 / fmaxf(lo_bf(gn[0]), 1e-30f); c1 = c1 / fmaxf(hi_bf(gn[0]), 1e-30f);
;                                 c2 = c2 / fmaxf(lo_bf(gn[1]), 1e-30f); c3 = c3 / fmaxf(hi_bf(gn[1]), 1e-30f);
;                                 acc[ai][bj][m][n][0] *= c0; acc[ai][bj][m][n][1] *= c1; acc[ai][bj][m][n][2] *= c2; acc[ai][bj][m][n][3] *= c3;
.LBB0_578:
	v_mov_b32_e32 v42, v174
	v_mov_b32_e32 v43, v175
	s_and_b64 vcc, exec, s[36:37]
	s_mov_b64 s[12:13], -1
	s_waitcnt vmcnt(0)
	v_lshlrev_b32_e32 v146, 16, v42
	v_and_b32_e32 v147, 0xffff0000, v42
	v_lshlrev_b32_e32 v142, 16, v43
	v_and_b32_e32 v143, 0xffff0000, v43
	s_cbranch_vccnz .LBB0_580
	v_mov_b32_e32 v42, v176
	v_mov_b32_e32 v43, v177
	s_waitcnt vmcnt(0)
	v_lshlrev_b32_e32 v1, 16, v42
	v_and_b32_e32 v42, 0xffff0000, v42
	v_max_f32_e32 v42, v42, v42
	v_lshlrev_b32_e32 v44, 16, v43
	v_and_b32_e32 v43, 0xffff0000, v43
	v_max_f32_e32 v42, 0xda24260, v42
	v_max_f32_e32 v43, v43, v43
	v_max_f32_e32 v45, 0xda24260, v43
	v_div_scale_f32 v43, s[12:13], v42, v42, v147
	v_rcp_f32_e32 v137, v43
	v_max_f32_e32 v1, v1, v1
	v_max_f32_e32 v1, 0xda24260, v1
	v_max_f32_e32 v44, v44, v44
	v_fma_f32 v144, -v43, v137, 1.0
	v_fmac_f32_e32 v137, v144, v137
	v_div_scale_f32 v144, vcc, v147, v42, v147
	v_mul_f32_e32 v148, v144, v137
	v_fma_f32 v149, -v43, v148, v144
	v_fmac_f32_e32 v148, v149, v137
	v_fma_f32 v43, -v43, v148, v144
	v_div_fmas_f32 v43, v43, v137, v148
	v_div_fixup_f32 v43, v43, v42, v147
	v_div_scale_f32 v42, s[12:13], v1, v1, v146
	v_rcp_f32_e32 v137, v42
	v_max_f32_e32 v44, 0xda24260, v44
	v_fma_f32 v144, -v42, v137, 1.0
	v_fmac_f32_e32 v137, v144, v137
	v_div_scale_f32 v144, vcc, v146, v1, v146
	v_mul_f32_e32 v148, v144, v137
	v_fma_f32 v149, -v42, v148, v144
	v_fmac_f32_e32 v148, v149, v137
	v_fma_f32 v42, -v42, v148, v144
	v_div_fmas_f32 v42, v42, v137, v148
	v_div_fixup_f32 v42, v42, v1, v146
	v_div_scale_f32 v1, s[12:13], v45, v45, v143
	v_rcp_f32_e32 v137, v1
	v_pk_mul_f32 v[42:43], v[50:51], v[42:43]
	v_fma_f32 v144, -v1, v137, 1.0
	v_fmac_f32_e32 v137, v144, v137
	v_div_scale_f32 v144, vcc, v143, v45, v143
	v_mul_f32_e32 v148, v144, v137
	v_fma_f32 v149, -v1, v148, v144
	v_fmac_f32_e32 v148, v149, v137
	v_fma_f32 v1, -v1, v148, v144
	v_div_fmas_f32 v1, v1, v137, v148
	v_div_fixup_f32 v45, v1, v45, v143
	v_div_scale_f32 v1, s[12:13], v44, v44, v142
	v_rcp_f32_e32 v137, v1
	s_mov_b64 s[12:13], 0
	v_fma_f32 v144, -v1, v137, 1.0
	v_fmac_f32_e32 v137, v144, v137
	v_div_scale_f32 v144, vcc, v142, v44, v142
	v_mul_f32_e32 v148, v144, v137
	v_fma_f32 v149, -v1, v148, v144
	v_fmac_f32_e32 v148, v149, v137
	v_fma_f32 v1, -v1, v148, v144
	v_div_fmas_f32 v1, v1, v137, v148
	v_div_fixup_f32 v44, v1, v44, v142
	v_pk_mul_f32 v[44:45], v[52:53], v[44:45]

; __device__ __forceinline__ float lo_bf(unsigned u) { return __uint_as_float(u << 16); }
; __device__ __forceinline__ float hi_bf(unsigned u) { return __uint_as_float(u & 0xffff0000u); }
; __device__ __forceinline__ void phase_merge(const Ctx& a, LAS unsigned char* lds) {
;     ...
;                             const bf16_t* gp = g + (size_t)row * NG + col;
;                             u32x2 gc = *(const u32x2*)(gp + seg * DM);
;                             float c0 = lo_bf(gc[0]), c1 = hi_bf(gc[0]), c2 = lo_bf(gc[1]), c3 = hi_bf(gc[1]);
;                             if (seg < 2) {
;                                 u32x2 gn = *(const u32x2*)(gp + (seg + 1) * DM);
;                                 c0 = c0 / fmaxf(lo_bf(gn[0]), 1e-30f); c1 = c1 / fmaxf(hi_bf(gn[0]), 1e-30f);
;                                 c2 = c2 / fmaxf(lo_bf(gn[1]), 1e-30f); c3 = c3 / fmaxf(hi_bf(gn[1]), 1e-30f);
;                                 acc[ai][bj][m][n][0] *= c0; acc[ai][bj][m][n][1] *= c1; acc[ai][bj][m][n][2] *= c2; acc[ai][bj][m][n][3] *= c3;
.LBB0_582:
	v_mov_b32_e32 v50, v184
	v_mov_b32_e32 v51, v185
	s_and_b64 vcc, exec, s[36:37]
	s_mov_b64 s[12:13], -1
	s_waitcnt vmcnt(0)
	v_lshlrev_b32_e32 v146, 16, v50
	v_and_b32_e32 v147, 0xffff0000, v50
	v_lshlrev_b32_e32 v142, 16, v51
	v_and_b32_e32 v143, 0xffff0000, v51
	s_cbranch_vccnz .LBB0_584
	v_mov_b32_e32 v50, v186
	v_mov_b32_e32 v51, v187
	s_waitcnt vmcnt(0)
	v_lshlrev_b32_e32 v1, 16, v50
	v_and_b32_e32 v50, 0xffff0000, v50
	v_max_f32_e32 v50, v50, v50
	v_lshlrev_b32_e32 v52, 16, v51
	v_and_b32_e32 v51, 0xffff0000, v51
	v_max_f32_e32 v50, 0xda24260, v50
	v_max_f32_e32 v51, v51, v51
	v_max_f32_e32 v53, 0xda24260, v51
	v_div_scale_f32 v51, s[12:13], v50, v50, v147
	v_rcp_f32_e32 v137, v51
	v_max_f32_e32 v1, v1, v1
	v_max_f32_e32 v1, 0xda24260, v1
	v_max_f32_e32 v52, v52, v52
	v_fma_f32 v144, -v51, v137, 1.0
	v_fmac_f32_e32 v137, v144, v137
	v_div_scale_f32 v144, vcc, v147, v50, v147
	v_mul_f32_e32 v148, v144, v137
	v_fma_f32 v149, -v51, v148, v144
	v_fmac_f32_e32 v148, v149, v137
	v_fma_f32 v51, -v51, v148, v144
	v_div_fmas_f32 v51, v51, v137, v148
	v_div_fixup_f32 v51, v51, v50, v147
	v_div_scale_f32 v50, s[12:13], v1, v1, v146
	v_rcp_f32_e32 v137, v50
	v_max_f32_e32 v52, 0xda24260, v52
	v_fma_f32 v144, -v50, v137, 1.0
	v_fmac_f32_e32 v137, v144, v137
	v_div_scale_f32 v144, vcc, v146, v1, v146
	v_mul_f32_e32 v148, v144, v137
	v_fma_f32 v149, -v50, v148, v144
	v_fmac_f32_e32 v148, v149, v137
	v_fma_f32 v50, -v50, v148, v144
	v_div_fmas_f32 v50, v50, v137, v148
	v_div_fixup_f32 v50, v50, v1, v146
	v_div_scale_f32 v1, s[12:13], v53, v53, v143
	v_rcp_f32_e32 v137, v1
	v_pk_mul_f32 v[50:51], v[58:59], v[50:51]
	v_fma_f32 v144, -v1, v137, 1.0
	v_fmac_f32_e32 v137, v144, v137
	v_div_scale_f32 v144, vcc, v143, v53, v143
	v_mul_f32_e32 v148, v144, v137
	v_fma_f32 v149, -v1, v148, v144
	v_fmac_f32_e32 v148, v149, v137
	v_fma_f32 v1, -v1, v148, v144
	v_div_fmas_f32 v1, v1, v137, v148
	v_div_fixup_f32 v53, v1, v53, v143
	v_div_scale_f32 v1, s[12:13], v52, v52, v142
	v_rcp_f32_e32 v137, v1
	s_mov_b64 s[12:13], 0
	v_fma_f32 v144, -v1, v137, 1.0
	v_fmac_f32_e32 v137, v144, v137
	v_div_scale_f32 v144, vcc, v142, v52, v142
	v_mul_f32_e32 v148, v144, v137
	v_fma_f32 v149, -v1, v148, v144
	v_fmac_f32_e32 v148, v149, v137
	v_fma_f32 v1, -v1, v148, v144
	v_div_fmas_f32 v1, v1, v137, v148
	v_div_fixup_f32 v52, v1, v52, v142
	v_pk_mul_f32 v[52:53], v[60:61], v[52:53]

; __device__ __forceinline__ float lo_bf(unsigned u) { return __uint_as_float(u << 16); }
; __device__ __forceinline__ float hi_bf(unsigned u) { return __uint_as_float(u & 0xffff0000u); }
; __device__ __forceinline__ void phase_merge(const Ctx& a, LAS unsigned char* lds) {
;     ...
;                             const bf16_t* gp = g + (size_t)row * NG + col;
;                             u32x2 gc = *(const u32x2*)(gp + seg * DM);
;                             float c0 = lo_bf(gc[0]), c1 = hi_bf(gc[0]), c2 = lo_bf(gc[1]), c3 = hi_bf(gc[1]);
;                             if (seg < 2) {
;                                 u32x2 gn = *(const u32x2*)(gp + (seg + 1) * DM);
;                                 c0 = c0 / fmaxf(lo_bf(gn[0]), 1e-30f); c1 = c1 / fmaxf(hi_bf(gn[0]), 1e-30f);
;                                 c2 = c2 / fmaxf(lo_bf(gn[1]), 1e-30f); c3 = c3 / fmaxf(hi_bf(gn[1]), 1e-30f);
;                                 acc[ai][bj][m][n][0] *= c0; acc[ai][bj][m][n][1] *= c1; acc[ai][bj][m][n][2] *= c2; acc[ai][bj][m][n][3] *= c3;
.LBB0_586:
	v_mov_b32_e32 v58, v188
	v_mov_b32_e32 v59, v189
	s_and_b64 vcc, exec, s[36:37]
	s_mov_b64 s[12:13], -1
	s_waitcnt vmcnt(0)
	v_lshlrev_b32_e32 v146, 16, v58
	v_and_b32_e32 v147, 0xffff0000, v58
	v_lshlrev_b32_e32 v142, 16, v59
	v_and_b32_e32 v143, 0xffff0000, v59
	s_cbranch_vccnz .LBB0_588
	v_mov_b32_e32 v58, v190
	v_mov_b32_e32 v59, v191
	s_waitcnt vmcnt(0)
	v_lshlrev_b32_e32 v1, 16, v58
	v_and_b32_e32 v58, 0xffff0000, v58
	v_max_f32_e32 v58, v58, v58
	v_lshlrev_b32_e32 v60, 16, v59
	v_and_b32_e32 v59, 0xffff0000, v59
	v_max_f32_e32 v58, 0xda24260, v58
	v_max_f32_e32 v59, v59, v59
	v_max_f32_e32 v61, 0xda24260, v59
	v_div_scale_f32 v59, s[12:13], v58, v58, v147
	v_rcp_f32_e32 v137, v59
	v_max_f32_e32 v1, v1, v1
	v_max_f32_e32 v1, 0xda24260, v1
	v_max_f32_e32 v60, v60, v60
	v_fma_f32 v138, -v59, v137, 1.0
	v_fmac_f32_e32 v137, v138, v137
	v_div_scale_f32 v138, vcc, v147, v58, v147
	v_mul_f32_e32 v139, v138, v137
	v_fma_f32 v144, -v59, v139, v138
	v_fmac_f32_e32 v139, v144, v137
	v_fma_f32 v59, -v59, v139, v138
	v_div_fmas_f32 v59, v59, v137, v139
	v_div_fixup_f32 v59, v59, v58, v147
	v_div_scale_f32 v58, s[12:13], v1, v1, v146
	v_rcp_f32_e32 v137, v58
	v_max_f32_e32 v60, 0xda24260, v60
	v_fma_f32 v138, -v58, v137, 1.0
	v_fmac_f32_e32 v137, v138, v137
	v_div_scale_f32 v138, vcc, v146, v1, v146
	v_mul_f32_e32 v139, v138, v137
	v_fma_f32 v144, -v58, v139, v138
	v_fmac_f32_e32 v139, v144, v137
	v_fma_f32 v58, -v58, v139, v138
	v_div_fmas_f32 v58, v58, v137, v139
	v_div_fixup_f32 v58, v58, v1, v146
	v_div_scale_f32 v1, s[12:13], v61, v61, v143
	v_rcp_f32_e32 v137, v1
	v_pk_mul_f32 v[58:59], v[66:67], v[58:59]
	v_fma_f32 v138, -v1, v137, 1.0
	v_fmac_f32_e32 v137, v138, v137
	v_div_scale_f32 v138, vcc, v143, v61, v143
	v_mul_f32_e32 v139, v138, v137
	v_fma_f32 v144, -v1, v139, v138
	v_fmac_f32_e32 v139, v144, v137
	v_fma_f32 v1, -v1, v139, v138
	v_div_fmas_f32 v1, v1, v137, v139
	v_div_fixup_f32 v61, v1, v61, v143
	v_div_scale_f32 v1, s[12:13], v60, v60, v142
	v_rcp_f32_e32 v137, v1
	s_mov_b64 s[12:13], 0
	v_fma_f32 v138, -v1, v137, 1.0
	v_fmac_f32_e32 v137, v138, v137
	v_div_scale_f32 v138, vcc, v142, v60, v142
	v_mul_f32_e32 v139, v138, v137
	v_fma_f32 v144, -v1, v139, v138
	v_fmac_f32_e32 v139, v144, v137
	v_fma_f32 v1, -v1, v139, v138
	v_div_fmas_f32 v1, v1, v137, v139
	v_div_fixup_f32 v60, v1, v60, v142
	v_pk_mul_f32 v[60:61], v[68:69], v[60:61]

; __device__ __forceinline__ float lo_bf(unsigned u) { return __uint_as_float(u << 16); }
; __device__ __forceinline__ float hi_bf(unsigned u) { return __uint_as_float(u & 0xffff0000u); }
; __device__ __forceinline__ void phase_merge(const Ctx& a, LAS unsigned char* lds) {
;     ...
;                     int row = pm * 256 + ai * 128 + t.wr * 64 + m * 16 + t.fr;
; #pragma unroll
;                     for (int bj = 0; bj < 2; ++bj)
; #pragma unroll
;                         for (int n = 0; n < 2; ++n) {
;                             int col = pn * 256 + bj * 128 + t.wc * 32 + n * 16 + t.fq * 4;
;                             const bf16_t* gp = g + (size_t)row * NG + col;
;                             u32x2 gc = *(const u32x2*)(gp + seg * DM);
;                             float c0 = lo_bf(gc[0]), c1 = hi_bf(gc[0]), c2 = lo_bf(gc[1]), c3 = hi_bf(gc[1]);
;                             if (seg < 2) {
;                                 u32x2 gn = *(const u32x2*)(gp + (seg + 1) * DM);
;                                 c0 = c0 / fmaxf(lo_bf(gn[0]), 1e-30f); c1 = c1 / fmaxf(hi_bf(gn[0]), 1e-30f);
;                                 c2 = c2 / fmaxf(lo_bf(gn[1]), 1e-30f); c3 = c3 / fmaxf(hi_bf(gn[1]), 1e-30f);
;                                 acc[ai][bj][m][n][0] *= c0; acc[ai][bj][m][n][1] *= c1; acc[ai][bj][m][n][2] *= c2; acc[ai][bj][m][n][3] *= c3;
.LBB0_590:
	v_or_b32_e32 v140, 32, v136
	v_mov_b64_e32 v[66:67], s[52:53]
	v_mad_i64_i32 v[66:67], s[12:13], v140, s84, v[66:67]
	v_lshl_add_u64 v[138:139], v[134:135], 1, v[66:67]
	v_mov_b32_e32 v66, v192
	v_mov_b32_e32 v67, v193
	s_and_b64 vcc, exec, s[36:37]
	s_mov_b64 s[12:13], -1
	s_waitcnt vmcnt(0)
	v_lshlrev_b32_e32 v146, 16, v66
	v_and_b32_e32 v147, 0xffff0000, v66
	v_lshlrev_b32_e32 v142, 16, v67
	v_and_b32_e32 v143, 0xffff0000, v67
	s_cbranch_vccnz .LBB0_592
	v_mov_b32_e32 v66, v200
	v_mov_b32_e32 v67, v201
	s_waitcnt vmcnt(0)
	v_lshlrev_b32_e32 v1, 16, v66
	v_and_b32_e32 v66, 0xffff0000, v66
	v_max_f32_e32 v66, v66, v66
	v_lshlrev_b32_e32 v68, 16, v67
	v_and_b32_e32 v67, 0xffff0000, v67
	v_max_f32_e32 v66, 0xda24260, v66
	v_max_f32_e32 v67, v67, v67
	v_max_f32_e32 v69, 0xda24260, v67
	v_div_scale_f32 v67, s[12:13], v66, v66, v147
	v_rcp_f32_e32 v137, v67
	v_max_f32_e32 v1, v1, v1
	v_max_f32_e32 v1, 0xda24260, v1
	v_max_f32_e32 v68, v68, v68
	v_fma_f32 v141, -v67, v137, 1.0
	v_fmac_f32_e32 v137, v141, v137
	v_div_scale_f32 v141, vcc, v147, v66, v147
	v_mul_f32_e32 v144, v141, v137
	v_fma_f32 v148, -v67, v144, v141
	v_fmac_f32_e32 v144, v148, v137
	v_fma_f32 v67, -v67, v144, v141
	v_div_fmas_f32 v67, v67, v137, v144
	v_div_fixup_f32 v67, v67, v66, v147
	v_div_scale_f32 v66, s[12:13], v1, v1, v146
	v_rcp_f32_e32 v137, v66
	v_max_f32_e32 v68, 0xda24260, v68
	v_fma_f32 v141, -v66, v137, 1.0
	v_fmac_f32_e32 v137, v141, v137
	v_div_scale_f32 v141, vcc, v146, v1, v146
	v_mul_f32_e32 v144, v141, v137
	v_fma_f32 v148, -v66, v144, v141
	v_fmac_f32_e32 v144, v148, v137
	v_fma_f32 v66, -v66, v144, v141
	v_div_fmas_f32 v66, v66, v137, v144
	v_div_fixup_f32 v66, v66, v1, v146
	v_div_scale_f32 v1, s[12:13], v69, v69, v143
	v_rcp_f32_e32 v137, v1
	v_pk_mul_f32 v[66:67], v[74:75], v[66:67]
	v_fma_f32 v141, -v1, v137, 1.0
	v_fmac_f32_e32 v137, v141, v137
	v_div_scale_f32 v141, vcc, v143, v69, v143
	v_mul_f32_e32 v144, v141, v137
	v_fma_f32 v148, -v1, v144, v141
	v_fmac_f32_e32 v144, v148, v137
	v_fma_f32 v1, -v1, v144, v141
	v_div_fmas_f32 v1, v1, v137, v144
	v_div_fixup_f32 v69, v1, v69, v143
	v_div_scale_f32 v1, s[12:13], v68, v68, v142
	v_rcp_f32_e32 v137, v1
	s_mov_b64 s[12:13], 0
	v_fma_f32 v141, -v1, v137, 1.0
	v_fmac_f32_e32 v137, v141, v137
	v_div_scale_f32 v141, vcc, v142, v68, v142
	v_mul_f32_e32 v144, v141, v137
	v_fma_f32 v148, -v1, v144, v141
	v_fmac_f32_e32 v144, v148, v137
	v_fma_f32 v1, -v1, v144, v141
	v_div_fmas_f32 v1, v1, v137, v144
	v_div_fixup_f32 v68, v1, v68, v142
	v_pk_mul_f32 v[68:69], v[76:77], v[68:69]

; __device__ __forceinline__ float lo_bf(unsigned u) { return __uint_as_float(u << 16); }
; __device__ __forceinline__ float hi_bf(unsigned u) { return __uint_as_float(u & 0xffff0000u); }
; __device__ __forceinline__ void phase_merge(const Ctx& a, LAS unsigned char* lds) {
;     ...
;                             const bf16_t* gp = g + (size_t)row * NG + col;
;                             u32x2 gc = *(const u32x2*)(gp + seg * DM);
;                             float c0 = lo_bf(gc[0]), c1 = hi_bf(gc[0]), c2 = lo_bf(gc[1]), c3 = hi_bf(gc[1]);
;                             if (seg < 2) {
;                                 u32x2 gn = *(const u32x2*)(gp + (seg + 1) * DM);
;                                 c0 = c0 / fmaxf(lo_bf(gn[0]), 1e-30f); c1 = c1 / fmaxf(hi_bf(gn[0]), 1e-30f);
;                                 c2 = c2 / fmaxf(lo_bf(gn[1]), 1e-30f); c3 = c3 / fmaxf(hi_bf(gn[1]), 1e-30f);
;                                 acc[ai][bj][m][n][0] *= c0; acc[ai][bj][m][n][1] *= c1; acc[ai][bj][m][n][2] *= c2; acc[ai][bj][m][n][3] *= c3;
.LBB0_594:
	v_mov_b32_e32 v74, v202
	v_mov_b32_e32 v75, v203
	s_and_b64 vcc, exec, s[36:37]
	s_mov_b64 s[12:13], -1
	s_waitcnt vmcnt(0)
	v_lshlrev_b32_e32 v146, 16, v74
	v_and_b32_e32 v147, 0xffff0000, v74
	v_lshlrev_b32_e32 v142, 16, v75
	v_and_b32_e32 v143, 0xffff0000, v75
	s_cbranch_vccnz .LBB0_596
	v_mov_b32_e32 v74, v204
	v_mov_b32_e32 v75, v205
	s_waitcnt vmcnt(0)
	v_lshlrev_b32_e32 v1, 16, v74
	v_and_b32_e32 v74, 0xffff0000, v74
	v_max_f32_e32 v74, v74, v74
	v_lshlrev_b32_e32 v76, 16, v75
	v_and_b32_e32 v75, 0xffff0000, v75
	v_max_f32_e32 v74, 0xda24260, v74
	v_max_f32_e32 v75, v75, v75
	v_max_f32_e32 v77, 0xda24260, v75
	v_div_scale_f32 v75, s[12:13], v74, v74, v147
	v_rcp_f32_e32 v137, v75
	v_max_f32_e32 v1, v1, v1
	v_max_f32_e32 v1, 0xda24260, v1
	v_max_f32_e32 v76, v76, v76
	v_fma_f32 v144, -v75, v137, 1.0
	v_fmac_f32_e32 v137, v144, v137
	v_div_scale_f32 v144, vcc, v147, v74, v147
	v_mul_f32_e32 v148, v144, v137
	v_fma_f32 v149, -v75, v148, v144
	v_fmac_f32_e32 v148, v149, v137
	v_fma_f32 v75, -v75, v148, v144
	v_div_fmas_f32 v75, v75, v137, v148
	v_div_fixup_f32 v75, v75, v74, v147
	v_div_scale_f32 v74, s[12:13], v1, v1, v146
	v_rcp_f32_e32 v137, v74
	v_max_f32_e32 v76, 0xda24260, v76
	v_fma_f32 v144, -v74, v137, 1.0
	v_fmac_f32_e32 v137, v144, v137
	v_div_scale_f32 v144, vcc, v146, v1, v146
	v_mul_f32_e32 v148, v144, v137
	v_fma_f32 v149, -v74, v148, v144
	v_fmac_f32_e32 v148, v149, v137
	v_fma_f32 v74, -v74, v148, v144
	v_div_fmas_f32 v74, v74, v137, v148
	v_div_fixup_f32 v74, v74, v1, v146
	v_div_scale_f32 v1, s[12:13], v77, v77, v143
	v_rcp_f32_e32 v137, v1
	v_pk_mul_f32 v[74:75], v[82:83], v[74:75]
	v_fma_f32 v144, -v1, v137, 1.0
	v_fmac_f32_e32 v137, v144, v137
	v_div_scale_f32 v144, vcc, v143, v77, v143
	v_mul_f32_e32 v148, v144, v137
	v_fma_f32 v149, -v1, v148, v144
	v_fmac_f32_e32 v148, v149, v137
	v_fma_f32 v1, -v1, v148, v144
	v_div_fmas_f32 v1, v1, v137, v148
	v_div_fixup_f32 v77, v1, v77, v143
	v_div_scale_f32 v1, s[12:13], v76, v76, v142
	v_rcp_f32_e32 v137, v1
	s_mov_b64 s[12:13], 0
	v_fma_f32 v144, -v1, v137, 1.0
	v_fmac_f32_e32 v137, v144, v137
	v_div_scale_f32 v144, vcc, v142, v76, v142
	v_mul_f32_e32 v148, v144, v137
	v_fma_f32 v149, -v1, v148, v144
	v_fmac_f32_e32 v148, v149, v137
	v_fma_f32 v1, -v1, v148, v144
	v_div_fmas_f32 v1, v1, v137, v148
	v_div_fixup_f32 v76, v1, v76, v142
	v_pk_mul_f32 v[76:77], v[84:85], v[76:77]

; __device__ __forceinline__ float lo_bf(unsigned u) { return __uint_as_float(u << 16); }
; __device__ __forceinline__ float hi_bf(unsigned u) { return __uint_as_float(u & 0xffff0000u); }
; __device__ __forceinline__ void phase_merge(const Ctx& a, LAS unsigned char* lds) {
;     ...
;                             const bf16_t* gp = g + (size_t)row * NG + col;
;                             u32x2 gc = *(const u32x2*)(gp + seg * DM);
;                             float c0 = lo_bf(gc[0]), c1 = hi_bf(gc[0]), c2 = lo_bf(gc[1]), c3 = hi_bf(gc[1]);
;                             if (seg < 2) {
;                                 u32x2 gn = *(const u32x2*)(gp + (seg + 1) * DM);
;                                 c0 = c0 / fmaxf(lo_bf(gn[0]), 1e-30f); c1 = c1 / fmaxf(hi_bf(gn[0]), 1e-30f);
;                                 c2 = c2 / fmaxf(lo_bf(gn[1]), 1e-30f); c3 = c3 / fmaxf(hi_bf(gn[1]), 1e-30f);
;                                 acc[ai][bj][m][n][0] *= c0; acc[ai][bj][m][n][1] *= c1; acc[ai][bj][m][n][2] *= c2; acc[ai][bj][m][n][3] *= c3;
.LBB0_598:
	v_mov_b32_e32 v82, v206
	v_mov_b32_e32 v83, v207
	s_and_b64 vcc, exec, s[36:37]
	s_mov_b64 s[12:13], -1
	s_waitcnt vmcnt(0)
	v_lshlrev_b32_e32 v146, 16, v82
	v_and_b32_e32 v147, 0xffff0000, v82
	v_lshlrev_b32_e32 v142, 16, v83
	v_and_b32_e32 v143, 0xffff0000, v83
	s_cbranch_vccnz .LBB0_600
	v_mov_b32_e32 v82, v208
	v_mov_b32_e32 v83, v209
	s_waitcnt vmcnt(0)
	v_lshlrev_b32_e32 v1, 16, v82
	v_and_b32_e32 v82, 0xffff0000, v82
	v_max_f32_e32 v82, v82, v82
	v_lshlrev_b32_e32 v84, 16, v83
	v_and_b32_e32 v83, 0xffff0000, v83
	v_max_f32_e32 v82, 0xda24260, v82
	v_max_f32_e32 v83, v83, v83
	v_max_f32_e32 v85, 0xda24260, v83
	v_div_scale_f32 v83, s[12:13], v82, v82, v147
	v_rcp_f32_e32 v137, v83
	v_max_f32_e32 v1, v1, v1
	v_max_f32_e32 v1, 0xda24260, v1
	v_max_f32_e32 v84, v84, v84
	v_fma_f32 v144, -v83, v137, 1.0
	v_fmac_f32_e32 v137, v144, v137
	v_div_scale_f32 v144, vcc, v147, v82, v147
	v_mul_f32_e32 v148, v144, v137
	v_fma_f32 v149, -v83, v148, v144
	v_fmac_f32_e32 v148, v149, v137
	v_fma_f32 v83, -v83, v148, v144
	v_div_fmas_f32 v83, v83, v137, v148
	v_div_fixup_f32 v83, v83, v82, v147
	v_div_scale_f32 v82, s[12:13], v1, v1, v146
	v_rcp_f32_e32 v137, v82
	v_max_f32_e32 v84, 0xda24260, v84
	v_fma_f32 v144, -v82, v137, 1.0
	v_fmac_f32_e32 v137, v144, v137
	v_div_scale_f32 v144, vcc, v146, v1, v146
	v_mul_f32_e32 v148, v144, v137
	v_fma_f32 v149, -v82, v148, v144
	v_fmac_f32_e32 v148, v149, v137
	v_fma_f32 v82, -v82, v148, v144
	v_div_fmas_f32 v82, v82, v137, v148
	v_div_fixup_f32 v82, v82, v1, v146
	v_div_scale_f32 v1, s[12:13], v85, v85, v143
	v_rcp_f32_e32 v137, v1
	v_pk_mul_f32 v[82:83], v[90:91], v[82:83]
	v_fma_f32 v144, -v1, v137, 1.0
	v_fmac_f32_e32 v137, v144, v137
	v_div_scale_f32 v144, vcc, v143, v85, v143
	v_mul_f32_e32 v148, v144, v137
	v_fma_f32 v149, -v1, v148, v144
	v_fmac_f32_e32 v148, v149, v137
	v_fma_f32 v1, -v1, v148, v144
	v_div_fmas_f32 v1, v1, v137, v148
	v_div_fixup_f32 v85, v1, v85, v143
	v_div_scale_f32 v1, s[12:13], v84, v84, v142
	v_rcp_f32_e32 v137, v1
	s_mov_b64 s[12:13], 0
	v_fma_f32 v144, -v1, v137, 1.0
	v_fmac_f32_e32 v137, v144, v137
	v_div_scale_f32 v144, vcc, v142, v84, v142
	v_mul_f32_e32 v148, v144, v137
	v_fma_f32 v149, -v1, v148, v144
	v_fmac_f32_e32 v148, v149, v137
	v_fma_f32 v1, -v1, v148, v144
	v_div_fmas_f32 v1, v1, v137, v148
	v_div_fixup_f32 v84, v1, v84, v142
	v_pk_mul_f32 v[84:85], v[92:93], v[84:85]

; __device__ __forceinline__ float lo_bf(unsigned u) { return __uint_as_float(u << 16); }
; __device__ __forceinline__ float hi_bf(unsigned u) { return __uint_as_float(u & 0xffff0000u); }
; __device__ __forceinline__ void phase_merge(const Ctx& a, LAS unsigned char* lds) {
;     ...
;                             const bf16_t* gp = g + (size_t)row * NG + col;
;                             u32x2 gc = *(const u32x2*)(gp + seg * DM);
;                             float c0 = lo_bf(gc[0]), c1 = hi_bf(gc[0]), c2 = lo_bf(gc[1]), c3 = hi_bf(gc[1]);
;                             if (seg < 2) {
;                                 u32x2 gn = *(const u32x2*)(gp + (seg + 1) * DM);
;                                 c0 = c0 / fmaxf(lo_bf(gn[0]), 1e-30f); c1 = c1 / fmaxf(hi_bf(gn[0]), 1e-30f);
;                                 c2 = c2 / fmaxf(lo_bf(gn[1]), 1e-30f); c3 = c3 / fmaxf(hi_bf(gn[1]), 1e-30f);
;                                 acc[ai][bj][m][n][0] *= c0; acc[ai][bj][m][n][1] *= c1; acc[ai][bj][m][n][2] *= c2; acc[ai][bj][m][n][3] *= c3;
.LBB0_602:
	v_mov_b32_e32 v90, v210
	v_mov_b32_e32 v91, v211
	s_and_b64 vcc, exec, s[36:37]
	s_mov_b64 s[12:13], -1
	s_waitcnt vmcnt(0)
	v_lshlrev_b32_e32 v146, 16, v90
	v_and_b32_e32 v147, 0xffff0000, v90
	v_lshlrev_b32_e32 v142, 16, v91
	v_and_b32_e32 v143, 0xffff0000, v91
	s_cbranch_vccnz .LBB0_604
	v_mov_b32_e32 v90, v212
	v_mov_b32_e32 v91, v213
	s_waitcnt vmcnt(0)
	v_lshlrev_b32_e32 v1, 16, v90
	v_and_b32_e32 v90, 0xffff0000, v90
	v_max_f32_e32 v90, v90, v90
	v_lshlrev_b32_e32 v92, 16, v91
	v_and_b32_e32 v91, 0xffff0000, v91
	v_max_f32_e32 v90, 0xda24260, v90
	v_max_f32_e32 v91, v91, v91
	v_max_f32_e32 v93, 0xda24260, v91
	v_div_scale_f32 v91, s[12:13], v90, v90, v147
	v_rcp_f32_e32 v137, v91
	v_max_f32_e32 v1, v1, v1
	v_max_f32_e32 v1, 0xda24260, v1
	v_max_f32_e32 v92, v92, v92
	v_fma_f32 v138, -v91, v137, 1.0
	v_fmac_f32_e32 v137, v138, v137
	v_div_scale_f32 v138, vcc, v147, v90, v147
	v_mul_f32_e32 v139, v138, v137
	v_fma_f32 v144, -v91, v139, v138
	v_fmac_f32_e32 v139, v144, v137
	v_fma_f32 v91, -v91, v139, v138
	v_div_fmas_f32 v91, v91, v137, v139
	v_div_fixup_f32 v91, v91, v90, v147
	v_div_scale_f32 v90, s[12:13], v1, v1, v146
	v_rcp_f32_e32 v137, v90
	v_max_f32_e32 v92, 0xda24260, v92
	v_fma_f32 v138, -v90, v137, 1.0
	v_fmac_f32_e32 v137, v138, v137
	v_div_scale_f32 v138, vcc, v146, v1, v146
	v_mul_f32_e32 v139, v138, v137
	v_fma_f32 v144, -v90, v139, v138
	v_fmac_f32_e32 v139, v144, v137
	v_fma_f32 v90, -v90, v139, v138
	v_div_fmas_f32 v90, v90, v137, v139
	v_div_fixup_f32 v90, v90, v1, v146
	v_div_scale_f32 v1, s[12:13], v93, v93, v143
	v_rcp_f32_e32 v137, v1
	v_pk_mul_f32 v[90:91], v[98:99], v[90:91]
	v_fma_f32 v138, -v1, v137, 1.0
	v_fmac_f32_e32 v137, v138, v137
	v_div_scale_f32 v138, vcc, v143, v93, v143
	v_mul_f32_e32 v139, v138, v137
	v_fma_f32 v144, -v1, v139, v138
	v_fmac_f32_e32 v139, v144, v137
	v_fma_f32 v1, -v1, v139, v138
	v_div_fmas_f32 v1, v1, v137, v139
	v_div_fixup_f32 v93, v1, v93, v143
	v_div_scale_f32 v1, s[12:13], v92, v92, v142
	v_rcp_f32_e32 v137, v1
	s_mov_b64 s[12:13], 0
	v_fma_f32 v138, -v1, v137, 1.0
	v_fmac_f32_e32 v137, v138, v137
	v_div_scale_f32 v138, vcc, v142, v92, v142
	v_mul_f32_e32 v139, v138, v137
	v_fma_f32 v144, -v1, v139, v138
	v_fmac_f32_e32 v139, v144, v137
	v_fma_f32 v1, -v1, v139, v138
	v_div_fmas_f32 v1, v1, v137, v139
	v_div_fixup_f32 v92, v1, v92, v142
	v_pk_mul_f32 v[92:93], v[100:101], v[92:93]

; __device__ __forceinline__ float lo_bf(unsigned u) { return __uint_as_float(u << 16); }
; __device__ __forceinline__ float hi_bf(unsigned u) { return __uint_as_float(u & 0xffff0000u); }
; __device__ __forceinline__ void phase_merge(const Ctx& a, LAS unsigned char* lds) {
;     ...
;                     int row = pm * 256 + ai * 128 + t.wr * 64 + m * 16 + t.fr;
; #pragma unroll
;                     for (int bj = 0; bj < 2; ++bj)
; #pragma unroll
;                         for (int n = 0; n < 2; ++n) {
;                             int col = pn * 256 + bj * 128 + t.wc * 32 + n * 16 + t.fq * 4;
;                             const bf16_t* gp = g + (size_t)row * NG + col;
;                             u32x2 gc = *(const u32x2*)(gp + seg * DM);
;                             float c0 = lo_bf(gc[0]), c1 = hi_bf(gc[0]), c2 = lo_bf(gc[1]), c3 = hi_bf(gc[1]);
;                             if (seg < 2) {
;                                 u32x2 gn = *(const u32x2*)(gp + (seg + 1) * DM);
;                                 c0 = c0 / fmaxf(lo_bf(gn[0]), 1e-30f); c1 = c1 / fmaxf(hi_bf(gn[0]), 1e-30f);
;                                 c2 = c2 / fmaxf(lo_bf(gn[1]), 1e-30f); c3 = c3 / fmaxf(hi_bf(gn[1]), 1e-30f);
;                                 acc[ai][bj][m][n][0] *= c0; acc[ai][bj][m][n][1] *= c1; acc[ai][bj][m][n][2] *= c2; acc[ai][bj][m][n][3] *= c3;
.LBB0_606:
	v_or_b32_e32 v140, 48, v136
	v_mov_b64_e32 v[98:99], s[52:53]
	v_mad_i64_i32 v[98:99], s[12:13], v140, s84, v[98:99]
	v_lshl_add_u64 v[138:139], v[134:135], 1, v[98:99]
	v_mov_b32_e32 v98, v214
	v_mov_b32_e32 v99, v215
	s_and_b64 vcc, exec, s[36:37]
	s_mov_b64 s[12:13], -1
	s_waitcnt vmcnt(0)
	v_lshlrev_b32_e32 v146, 16, v98
	v_and_b32_e32 v147, 0xffff0000, v98
	v_lshlrev_b32_e32 v142, 16, v99
	v_and_b32_e32 v143, 0xffff0000, v99
	s_cbranch_vccnz .LBB0_608
	v_mov_b32_e32 v98, v216
	v_mov_b32_e32 v99, v217
	s_waitcnt vmcnt(0)
	v_lshlrev_b32_e32 v1, 16, v98
	v_and_b32_e32 v98, 0xffff0000, v98
	v_max_f32_e32 v98, v98, v98
	v_lshlrev_b32_e32 v100, 16, v99
	v_and_b32_e32 v99, 0xffff0000, v99
	v_max_f32_e32 v98, 0xda24260, v98
	v_max_f32_e32 v99, v99, v99
	v_max_f32_e32 v101, 0xda24260, v99
	v_div_scale_f32 v99, s[12:13], v98, v98, v147
	v_rcp_f32_e32 v137, v99
	v_max_f32_e32 v1, v1, v1
	v_max_f32_e32 v1, 0xda24260, v1
	v_max_f32_e32 v100, v100, v100
	v_fma_f32 v141, -v99, v137, 1.0
	v_fmac_f32_e32 v137, v141, v137
	v_div_scale_f32 v141, vcc, v147, v98, v147
	v_mul_f32_e32 v144, v141, v137
	v_fma_f32 v148, -v99, v144, v141
	v_fmac_f32_e32 v144, v148, v137
	v_fma_f32 v99, -v99, v144, v141
	v_div_fmas_f32 v99, v99, v137, v144
	v_div_fixup_f32 v99, v99, v98, v147
	v_div_scale_f32 v98, s[12:13], v1, v1, v146
	v_rcp_f32_e32 v137, v98
	v_max_f32_e32 v100, 0xda24260, v100
	v_fma_f32 v141, -v98, v137, 1.0
	v_fmac_f32_e32 v137, v141, v137
	v_div_scale_f32 v141, vcc, v146, v1, v146
	v_mul_f32_e32 v144, v141, v137
	v_fma_f32 v148, -v98, v144, v141
	v_fmac_f32_e32 v144, v148, v137
	v_fma_f32 v98, -v98, v144, v141
	v_div_fmas_f32 v98, v98, v137, v144
	v_div_fixup_f32 v98, v98, v1, v146
	v_div_scale_f32 v1, s[12:13], v101, v101, v143
	v_rcp_f32_e32 v137, v1
	v_pk_mul_f32 v[98:99], v[106:107], v[98:99]
	v_fma_f32 v141, -v1, v137, 1.0
	v_fmac_f32_e32 v137, v141, v137
	v_div_scale_f32 v141, vcc, v143, v101, v143
	v_mul_f32_e32 v144, v141, v137
	v_fma_f32 v148, -v1, v144, v141
	v_fmac_f32_e32 v144, v148, v137
	v_fma_f32 v1, -v1, v144, v141
	v_div_fmas_f32 v1, v1, v137, v144
	v_div_fixup_f32 v101, v1, v101, v143
	v_div_scale_f32 v1, s[12:13], v100, v100, v142
	v_rcp_f32_e32 v137, v1
	s_mov_b64 s[12:13], 0
	v_fma_f32 v141, -v1, v137, 1.0
	v_fmac_f32_e32 v137, v141, v137
	v_div_scale_f32 v141, vcc, v142, v100, v142
	v_mul_f32_e32 v144, v141, v137
	v_fma_f32 v148, -v1, v144, v141
	v_fmac_f32_e32 v144, v148, v137
	v_fma_f32 v1, -v1, v144, v141
	v_div_fmas_f32 v1, v1, v137, v144
	v_div_fixup_f32 v100, v1, v100, v142
	v_pk_mul_f32 v[100:101], v[108:109], v[100:101]

; __device__ __forceinline__ float lo_bf(unsigned u) { return __uint_as_float(u << 16); }
; __device__ __forceinline__ float hi_bf(unsigned u) { return __uint_as_float(u & 0xffff0000u); }
; __device__ __forceinline__ void phase_merge(const Ctx& a, LAS unsigned char* lds) {
;     ...
;                             const bf16_t* gp = g + (size_t)row * NG + col;
;                             u32x2 gc = *(const u32x2*)(gp + seg * DM);
;                             float c0 = lo_bf(gc[0]), c1 = hi_bf(gc[0]), c2 = lo_bf(gc[1]), c3 = hi_bf(gc[1]);
;                             if (seg < 2) {
;                                 u32x2 gn = *(const u32x2*)(gp + (seg + 1) * DM);
;                                 c0 = c0 / fmaxf(lo_bf(gn[0]), 1e-30f); c1 = c1 / fmaxf(hi_bf(gn[0]), 1e-30f);
;                                 c2 = c2 / fmaxf(lo_bf(gn[1]), 1e-30f); c3 = c3 / fmaxf(hi_bf(gn[1]), 1e-30f);
;                                 acc[ai][bj][m][n][0] *= c0; acc[ai][bj][m][n][1] *= c1; acc[ai][bj][m][n][2] *= c2; acc[ai][bj][m][n][3] *= c3;
.LBB0_610:
	v_mov_b32_e32 v106, v218
	v_mov_b32_e32 v107, v219
	s_and_b64 vcc, exec, s[36:37]
	s_mov_b64 s[12:13], -1
	s_waitcnt vmcnt(0)
	v_lshlrev_b32_e32 v146, 16, v106
	v_and_b32_e32 v147, 0xffff0000, v106
	v_lshlrev_b32_e32 v142, 16, v107
	v_and_b32_e32 v143, 0xffff0000, v107
	s_cbranch_vccnz .LBB0_612
	v_mov_b32_e32 v106, v220
	v_mov_b32_e32 v107, v221
	s_waitcnt vmcnt(0)
	v_lshlrev_b32_e32 v1, 16, v106
	v_and_b32_e32 v106, 0xffff0000, v106
	v_max_f32_e32 v106, v106, v106
	v_lshlrev_b32_e32 v108, 16, v107
	v_and_b32_e32 v107, 0xffff0000, v107
	v_max_f32_e32 v106, 0xda24260, v106
	v_max_f32_e32 v107, v107, v107
	v_max_f32_e32 v109, 0xda24260, v107
	v_div_scale_f32 v107, s[12:13], v106, v106, v147
	v_rcp_f32_e32 v137, v107
	v_max_f32_e32 v1, v1, v1
	v_max_f32_e32 v1, 0xda24260, v1
	v_max_f32_e32 v108, v108, v108
	v_fma_f32 v144, -v107, v137, 1.0
	v_fmac_f32_e32 v137, v144, v137
	v_div_scale_f32 v144, vcc, v147, v106, v147
	v_mul_f32_e32 v148, v144, v137
	v_fma_f32 v149, -v107, v148, v144
	v_fmac_f32_e32 v148, v149, v137
	v_fma_f32 v107, -v107, v148, v144
	v_div_fmas_f32 v107, v107, v137, v148
	v_div_fixup_f32 v107, v107, v106, v147
	v_div_scale_f32 v106, s[12:13], v1, v1, v146
	v_rcp_f32_e32 v137, v106
	v_max_f32_e32 v108, 0xda24260, v108
	v_fma_f32 v144, -v106, v137, 1.0
	v_fmac_f32_e32 v137, v144, v137
	v_div_scale_f32 v144, vcc, v146, v1, v146
	v_mul_f32_e32 v148, v144, v137
	v_fma_f32 v149, -v106, v148, v144
	v_fmac_f32_e32 v148, v149, v137
	v_fma_f32 v106, -v106, v148, v144
	v_div_fmas_f32 v106, v106, v137, v148
	v_div_fixup_f32 v106, v106, v1, v146
	v_div_scale_f32 v1, s[12:13], v109, v109, v143
	v_rcp_f32_e32 v137, v1
	v_pk_mul_f32 v[106:107], v[114:115], v[106:107]
	v_fma_f32 v144, -v1, v137, 1.0
	v_fmac_f32_e32 v137, v144, v137
	v_div_scale_f32 v144, vcc, v143, v109, v143
	v_mul_f32_e32 v148, v144, v137
	v_fma_f32 v149, -v1, v148, v144
	v_fmac_f32_e32 v148, v149, v137
	v_fma_f32 v1, -v1, v148, v144
	v_div_fmas_f32 v1, v1, v137, v148
	v_div_fixup_f32 v109, v1, v109, v143
	v_div_scale_f32 v1, s[12:13], v108, v108, v142
	v_rcp_f32_e32 v137, v1
	s_mov_b64 s[12:13], 0
	v_fma_f32 v144, -v1, v137, 1.0
	v_fmac_f32_e32 v137, v144, v137
	v_div_scale_f32 v144, vcc, v142, v108, v142
	v_mul_f32_e32 v148, v144, v137
	v_fma_f32 v149, -v1, v148, v144
	v_fmac_f32_e32 v148, v149, v137
	v_fma_f32 v1, -v1, v148, v144
	v_div_fmas_f32 v1, v1, v137, v148
	v_div_fixup_f32 v108, v1, v108, v142
	v_pk_mul_f32 v[108:109], v[116:117], v[108:109]

; __device__ __forceinline__ float lo_bf(unsigned u) { return __uint_as_float(u << 16); }
; __device__ __forceinline__ float hi_bf(unsigned u) { return __uint_as_float(u & 0xffff0000u); }
; __device__ __forceinline__ void phase_merge(const Ctx& a, LAS unsigned char* lds) {
;     ...
;                             const bf16_t* gp = g + (size_t)row * NG + col;
;                             u32x2 gc = *(const u32x2*)(gp + seg * DM);
;                             float c0 = lo_bf(gc[0]), c1 = hi_bf(gc[0]), c2 = lo_bf(gc[1]), c3 = hi_bf(gc[1]);
;                             if (seg < 2) {
;                                 u32x2 gn = *(const u32x2*)(gp + (seg + 1) * DM);
;                                 c0 = c0 / fmaxf(lo_bf(gn[0]), 1e-30f); c1 = c1 / fmaxf(hi_bf(gn[0]), 1e-30f);
;                                 c2 = c2 / fmaxf(lo_bf(gn[1]), 1e-30f); c3 = c3 / fmaxf(hi_bf(gn[1]), 1e-30f);
;                                 acc[ai][bj][m][n][0] *= c0; acc[ai][bj][m][n][1] *= c1; acc[ai][bj][m][n][2] *= c2; acc[ai][bj][m][n][3] *= c3;
.LBB0_614:
	v_mov_b32_e32 v114, v222
	v_mov_b32_e32 v115, v223
	s_and_b64 vcc, exec, s[36:37]
	s_mov_b64 s[12:13], -1
	s_waitcnt vmcnt(0)
	v_lshlrev_b32_e32 v146, 16, v114
	v_and_b32_e32 v147, 0xffff0000, v114
	v_lshlrev_b32_e32 v142, 16, v115
	v_and_b32_e32 v143, 0xffff0000, v115
	s_cbranch_vccnz .LBB0_616
	v_mov_b32_e32 v114, v224
	v_mov_b32_e32 v115, v225
	s_waitcnt vmcnt(0)
	v_lshlrev_b32_e32 v1, 16, v114
	v_and_b32_e32 v114, 0xffff0000, v114
	v_max_f32_e32 v114, v114, v114
	v_lshlrev_b32_e32 v116, 16, v115
	v_and_b32_e32 v115, 0xffff0000, v115
	v_max_f32_e32 v114, 0xda24260, v114
	v_max_f32_e32 v115, v115, v115
	v_max_f32_e32 v117, 0xda24260, v115
	v_div_scale_f32 v115, s[12:13], v114, v114, v147
	v_rcp_f32_e32 v137, v115
	v_max_f32_e32 v1, v1, v1
	v_max_f32_e32 v1, 0xda24260, v1
	v_max_f32_e32 v116, v116, v116
	v_fma_f32 v144, -v115, v137, 1.0
	v_fmac_f32_e32 v137, v144, v137
	v_div_scale_f32 v144, vcc, v147, v114, v147
	v_mul_f32_e32 v148, v144, v137
	v_fma_f32 v149, -v115, v148, v144
	v_fmac_f32_e32 v148, v149, v137
	v_fma_f32 v115, -v115, v148, v144
	v_div_fmas_f32 v115, v115, v137, v148
	v_div_fixup_f32 v115, v115, v114, v147
	v_div_scale_f32 v114, s[12:13], v1, v1, v146
	v_rcp_f32_e32 v137, v114
	v_max_f32_e32 v116, 0xda24260, v116
	v_fma_f32 v144, -v114, v137, 1.0
	v_fmac_f32_e32 v137, v144, v137
	v_div_scale_f32 v144, vcc, v146, v1, v146
	v_mul_f32_e32 v148, v144, v137
	v_fma_f32 v149, -v114, v148, v144
	v_fmac_f32_e32 v148, v149, v137
	v_fma_f32 v114, -v114, v148, v144
	v_div_fmas_f32 v114, v114, v137, v148
	v_div_fixup_f32 v114, v114, v1, v146
	v_div_scale_f32 v1, s[12:13], v117, v117, v143
	v_rcp_f32_e32 v137, v1
	v_pk_mul_f32 v[114:115], v[122:123], v[114:115]
	v_fma_f32 v144, -v1, v137, 1.0
	v_fmac_f32_e32 v137, v144, v137
	v_div_scale_f32 v144, vcc, v143, v117, v143
	v_mul_f32_e32 v148, v144, v137
	v_fma_f32 v149, -v1, v148, v144
	v_fmac_f32_e32 v148, v149, v137
	v_fma_f32 v1, -v1, v148, v144
	v_div_fmas_f32 v1, v1, v137, v148
	v_div_fixup_f32 v117, v1, v117, v143
	v_div_scale_f32 v1, s[12:13], v116, v116, v142
	v_rcp_f32_e32 v137, v1
	s_mov_b64 s[12:13], 0
	v_fma_f32 v144, -v1, v137, 1.0
	v_fmac_f32_e32 v137, v144, v137
	v_div_scale_f32 v144, vcc, v142, v116, v142
	v_mul_f32_e32 v148, v144, v137
	v_fma_f32 v149, -v1, v148, v144
	v_fmac_f32_e32 v148, v149, v137
	v_fma_f32 v1, -v1, v148, v144
	v_div_fmas_f32 v1, v1, v137, v148
	v_div_fixup_f32 v116, v1, v116, v142
	v_pk_mul_f32 v[116:117], v[124:125], v[116:117]

; __device__ __forceinline__ float lo_bf(unsigned u) { return __uint_as_float(u << 16); }
; __device__ __forceinline__ float hi_bf(unsigned u) { return __uint_as_float(u & 0xffff0000u); }
; __device__ __forceinline__ void phase_merge(const Ctx& a, LAS unsigned char* lds) {
;     ...
;                             const bf16_t* gp = g + (size_t)row * NG + col;
;                             u32x2 gc = *(const u32x2*)(gp + seg * DM);
;                             float c0 = lo_bf(gc[0]), c1 = hi_bf(gc[0]), c2 = lo_bf(gc[1]), c3 = hi_bf(gc[1]);
;                             if (seg < 2) {
;                                 u32x2 gn = *(const u32x2*)(gp + (seg + 1) * DM);
;                                 c0 = c0 / fmaxf(lo_bf(gn[0]), 1e-30f); c1 = c1 / fmaxf(hi_bf(gn[0]), 1e-30f);
;                                 c2 = c2 / fmaxf(lo_bf(gn[1]), 1e-30f); c3 = c3 / fmaxf(hi_bf(gn[1]), 1e-30f);
;                                 acc[ai][bj][m][n][0] *= c0; acc[ai][bj][m][n][1] *= c1; acc[ai][bj][m][n][2] *= c2; acc[ai][bj][m][n][3] *= c3;
.LBB0_618:
	v_mov_b32_e32 v122, v226
	v_mov_b32_e32 v123, v227
	s_and_b64 vcc, exec, s[36:37]
	s_mov_b64 s[12:13], -1
	s_waitcnt vmcnt(0)
	v_lshlrev_b32_e32 v146, 16, v122
	v_and_b32_e32 v147, 0xffff0000, v122
	v_lshlrev_b32_e32 v142, 16, v123
	v_and_b32_e32 v143, 0xffff0000, v123
	s_cbranch_vccnz .LBB0_620
	v_mov_b32_e32 v122, v228
	v_mov_b32_e32 v123, v229
	s_waitcnt vmcnt(0)
	v_lshlrev_b32_e32 v1, 16, v122
	v_and_b32_e32 v122, 0xffff0000, v122
	v_max_f32_e32 v122, v122, v122
	v_lshlrev_b32_e32 v124, 16, v123
	v_and_b32_e32 v123, 0xffff0000, v123
	v_max_f32_e32 v122, 0xda24260, v122
	v_max_f32_e32 v123, v123, v123
	v_max_f32_e32 v125, 0xda24260, v123
	v_div_scale_f32 v123, s[12:13], v122, v122, v147
	v_rcp_f32_e32 v137, v123
	v_max_f32_e32 v1, v1, v1
	v_max_f32_e32 v1, 0xda24260, v1
	v_max_f32_e32 v124, v124, v124
	v_fma_f32 v138, -v123, v137, 1.0
	v_fmac_f32_e32 v137, v138, v137
	v_div_scale_f32 v138, vcc, v147, v122, v147
	v_mul_f32_e32 v139, v138, v137
	v_fma_f32 v144, -v123, v139, v138
	v_fmac_f32_e32 v139, v144, v137
	v_fma_f32 v123, -v123, v139, v138
	v_div_fmas_f32 v123, v123, v137, v139
	v_div_fixup_f32 v123, v123, v122, v147
	v_div_scale_f32 v122, s[12:13], v1, v1, v146
	v_rcp_f32_e32 v137, v122
	v_max_f32_e32 v124, 0xda24260, v124
	v_fma_f32 v138, -v122, v137, 1.0
	v_fmac_f32_e32 v137, v138, v137
	v_div_scale_f32 v138, vcc, v146, v1, v146
	v_mul_f32_e32 v139, v138, v137
	v_fma_f32 v144, -v122, v139, v138
	v_fmac_f32_e32 v139, v144, v137
	v_fma_f32 v122, -v122, v139, v138
	v_div_fmas_f32 v122, v122, v137, v139
	v_div_fixup_f32 v122, v122, v1, v146
	v_div_scale_f32 v1, s[12:13], v125, v125, v143
	v_rcp_f32_e32 v137, v1
	v_pk_mul_f32 v[122:123], v[130:131], v[122:123]
	v_fma_f32 v138, -v1, v137, 1.0
	v_fmac_f32_e32 v137, v138, v137
	v_div_scale_f32 v138, vcc, v143, v125, v143
	v_mul_f32_e32 v139, v138, v137
	v_fma_f32 v144, -v1, v139, v138
	v_fmac_f32_e32 v139, v144, v137
	v_fma_f32 v1, -v1, v139, v138
	v_div_fmas_f32 v1, v1, v137, v139
	v_div_fixup_f32 v125, v1, v125, v143
	v_div_scale_f32 v1, s[12:13], v124, v124, v142
	v_rcp_f32_e32 v137, v1
	s_mov_b64 s[12:13], 0
	v_fma_f32 v138, -v1, v137, 1.0
	v_fmac_f32_e32 v137, v138, v137
	v_div_scale_f32 v138, vcc, v142, v124, v142
	v_mul_f32_e32 v139, v138, v137
	v_fma_f32 v144, -v1, v139, v138
	v_fmac_f32_e32 v139, v144, v137
	v_fma_f32 v1, -v1, v139, v138
	v_div_fmas_f32 v1, v1, v137, v139
	v_div_fixup_f32 v124, v1, v124, v142
	v_pk_mul_f32 v[124:125], v[132:133], v[124:125]

; __device__ __forceinline__ float lo_bf(unsigned u) { return __uint_as_float(u << 16); }
; __device__ __forceinline__ float hi_bf(unsigned u) { return __uint_as_float(u & 0xffff0000u); }
; __device__ __forceinline__ void phase_merge(const Ctx& a, LAS unsigned char* lds) {
;     ...
;                     int row = pm * 256 + ai * 128 + t.wr * 64 + m * 16 + t.fr;
; #pragma unroll
;                     for (int bj = 0; bj < 2; ++bj)
; #pragma unroll
;                         for (int n = 0; n < 2; ++n) {
;                             int col = pn * 256 + bj * 128 + t.wc * 32 + n * 16 + t.fq * 4;
;                             const bf16_t* gp = g + (size_t)row * NG + col;
;                             u32x2 gc = *(const u32x2*)(gp + seg * DM);
;                             float c0 = lo_bf(gc[0]), c1 = hi_bf(gc[0]), c2 = lo_bf(gc[1]), c3 = hi_bf(gc[1]);
;                             if (seg < 2) {
;                                 u32x2 gn = *(const u32x2*)(gp + (seg + 1) * DM);
;                                 c0 = c0 / fmaxf(lo_bf(gn[0]), 1e-30f); c1 = c1 / fmaxf(hi_bf(gn[0]), 1e-30f);
;                                 c2 = c2 / fmaxf(lo_bf(gn[1]), 1e-30f); c3 = c3 / fmaxf(hi_bf(gn[1]), 1e-30f);
;                                 acc[ai][bj][m][n][0] *= c0; acc[ai][bj][m][n][1] *= c1; acc[ai][bj][m][n][2] *= c2; acc[ai][bj][m][n][3] *= c3;
.LBB0_622:
	v_add_u32_e32 v140, 0x80, v136
	v_mov_b64_e32 v[130:131], s[52:53]
	v_mad_i64_i32 v[130:131], s[12:13], v140, s84, v[130:131]
	v_lshl_add_u64 v[138:139], v[134:135], 1, v[130:131]
	v_mov_b32_e32 v250, 0xc0000
	v_mov_b32_e32 v251, 0
	v_lshl_add_u64 v[152:153], v[250:251], 0, v[150:151]
	global_load_dwordx2 v[154:155], v[152:153], off
	global_load_dwordx2 v[156:157], v[152:153], off offset:2048
	global_load_dwordx2 v[158:159], v[152:153], off offset:32
	global_load_dwordx2 v[160:161], v[152:153], off offset:2080
	global_load_dwordx2 v[162:163], v[152:153], off offset:256
	global_load_dwordx2 v[164:165], v[152:153], off offset:2304
	global_load_dwordx2 v[166:167], v[152:153], off offset:288
	global_load_dwordx2 v[168:169], v[152:153], off offset:2336
	v_mov_b32_e32 v250, 0xd8000
	v_mov_b32_e32 v251, 0
	v_lshl_add_u64 v[152:153], v[250:251], 0, v[150:151]
	global_load_dwordx2 v[170:171], v[152:153], off
	global_load_dwordx2 v[172:173], v[152:153], off offset:2048
	global_load_dwordx2 v[174:175], v[152:153], off offset:32
	global_load_dwordx2 v[176:177], v[152:153], off offset:2080
	global_load_dwordx2 v[184:185], v[152:153], off offset:256
	global_load_dwordx2 v[186:187], v[152:153], off offset:2304
	global_load_dwordx2 v[188:189], v[152:153], off offset:288
	global_load_dwordx2 v[190:191], v[152:153], off offset:2336
	v_mov_b32_e32 v250, 0xf0000
	v_mov_b32_e32 v251, 0
	v_lshl_add_u64 v[152:153], v[250:251], 0, v[150:151]
	global_load_dwordx2 v[192:193], v[152:153], off
	global_load_dwordx2 v[200:201], v[152:153], off offset:2048
	global_load_dwordx2 v[202:203], v[152:153], off offset:32
	global_load_dwordx2 v[204:205], v[152:153], off offset:2080
	global_load_dwordx2 v[206:207], v[152:153], off offset:256
	global_load_dwordx2 v[208:209], v[152:153], off offset:2304
	global_load_dwordx2 v[210:211], v[152:153], off offset:288
	global_load_dwordx2 v[212:213], v[152:153], off offset:2336
	v_mov_b32_e32 v250, 0x108000
	v_mov_b32_e32 v251, 0
	v_lshl_add_u64 v[152:153], v[250:251], 0, v[150:151]
	global_load_dwordx2 v[214:215], v[152:153], off
	global_load_dwordx2 v[216:217], v[152:153], off offset:2048
	global_load_dwordx2 v[218:219], v[152:153], off offset:32
	global_load_dwordx2 v[220:221], v[152:153], off offset:2080
	global_load_dwordx2 v[222:223], v[152:153], off offset:256
	global_load_dwordx2 v[224:225], v[152:153], off offset:2304
	global_load_dwordx2 v[226:227], v[152:153], off offset:288
	global_load_dwordx2 v[228:229], v[152:153], off offset:2336
	s_waitcnt vmcnt(0)
	v_mov_b32_e32 v130, v154
	v_mov_b32_e32 v131, v155
	s_and_b64 vcc, exec, s[36:37]
	s_mov_b64 s[12:13], -1
	s_waitcnt vmcnt(0)
	v_lshlrev_b32_e32 v146, 16, v130
	v_and_b32_e32 v147, 0xffff0000, v130
	v_lshlrev_b32_e32 v142, 16, v131
	v_and_b32_e32 v143, 0xffff0000, v131
	s_cbranch_vccnz .LBB0_624
	v_mov_b32_e32 v130, v156
	v_mov_b32_e32 v131, v157
	s_waitcnt vmcnt(0)
	v_lshlrev_b32_e32 v1, 16, v130
	v_and_b32_e32 v130, 0xffff0000, v130
	v_max_f32_e32 v130, v130, v130
	v_lshlrev_b32_e32 v132, 16, v131
	v_and_b32_e32 v131, 0xffff0000, v131
	v_max_f32_e32 v130, 0xda24260, v130
	v_max_f32_e32 v131, v131, v131
	v_max_f32_e32 v133, 0xda24260, v131
	v_div_scale_f32 v131, s[12:13], v130, v130, v147
	v_rcp_f32_e32 v137, v131
	v_max_f32_e32 v1, v1, v1
	v_max_f32_e32 v1, 0xda24260, v1
	v_max_f32_e32 v132, v132, v132
	v_fma_f32 v141, -v131, v137, 1.0
	v_fmac_f32_e32 v137, v141, v137
	v_div_scale_f32 v141, vcc, v147, v130, v147
	v_mul_f32_e32 v144, v141, v137
	v_fma_f32 v148, -v131, v144, v141
	v_fmac_f32_e32 v144, v148, v137
	v_fma_f32 v131, -v131, v144, v141
	v_div_fmas_f32 v131, v131, v137, v144
	v_div_fixup_f32 v131, v131, v130, v147
	v_div_scale_f32 v130, s[12:13], v1, v1, v146
	v_rcp_f32_e32 v137, v130
	v_max_f32_e32 v132, 0xda24260, v132
	v_fma_f32 v141, -v130, v137, 1.0
	v_fmac_f32_e32 v137, v141, v137
	v_div_scale_f32 v141, vcc, v146, v1, v146
	v_mul_f32_e32 v144, v141, v137
	v_fma_f32 v148, -v130, v144, v141
	v_fmac_f32_e32 v144, v148, v137
	v_fma_f32 v130, -v130, v144, v141
	v_div_fmas_f32 v130, v130, v137, v144
	v_div_fixup_f32 v130, v130, v1, v146
	v_div_scale_f32 v1, s[12:13], v133, v133, v143
	v_rcp_f32_e32 v137, v1
	v_pk_mul_f32 v[130:131], v[126:127], v[130:131]
	v_fma_f32 v141, -v1, v137, 1.0
	v_fmac_f32_e32 v137, v141, v137
	v_div_scale_f32 v141, vcc, v143, v133, v143
	v_mul_f32_e32 v144, v141, v137
	v_fma_f32 v148, -v1, v144, v141
	v_fmac_f32_e32 v144, v148, v137
	v_fma_f32 v1, -v1, v144, v141
	v_div_fmas_f32 v1, v1, v137, v144
	v_div_fixup_f32 v133, v1, v133, v143
	v_div_scale_f32 v1, s[12:13], v132, v132, v142
	v_rcp_f32_e32 v137, v1
	s_mov_b64 s[12:13], 0
	v_fma_f32 v141, -v1, v137, 1.0
	v_fmac_f32_e32 v137, v141, v137
	v_div_scale_f32 v141, vcc, v142, v132, v142
	v_mul_f32_e32 v144, v141, v137
	v_fma_f32 v148, -v1, v144, v141
	v_fmac_f32_e32 v144, v148, v137
	v_fma_f32 v1, -v1, v144, v141
	v_div_fmas_f32 v1, v1, v137, v144
	v_div_fixup_f32 v132, v1, v132, v142
	v_pk_mul_f32 v[132:133], v[128:129], v[132:133]

; __device__ __forceinline__ float lo_bf(unsigned u) { return __uint_as_float(u << 16); }
; __device__ __forceinline__ float hi_bf(unsigned u) { return __uint_as_float(u & 0xffff0000u); }
; __device__ __forceinline__ void phase_merge(const Ctx& a, LAS unsigned char* lds) {
;     ...
;                             const bf16_t* gp = g + (size_t)row * NG + col;
;                             u32x2 gc = *(const u32x2*)(gp + seg * DM);
;                             float c0 = lo_bf(gc[0]), c1 = hi_bf(gc[0]), c2 = lo_bf(gc[1]), c3 = hi_bf(gc[1]);
;                             if (seg < 2) {
;                                 u32x2 gn = *(const u32x2*)(gp + (seg + 1) * DM);
;                                 c0 = c0 / fmaxf(lo_bf(gn[0]), 1e-30f); c1 = c1 / fmaxf(hi_bf(gn[0]), 1e-30f);
;                                 c2 = c2 / fmaxf(lo_bf(gn[1]), 1e-30f); c3 = c3 / fmaxf(hi_bf(gn[1]), 1e-30f);
;                                 acc[ai][bj][m][n][0] *= c0; acc[ai][bj][m][n][1] *= c1; acc[ai][bj][m][n][2] *= c2; acc[ai][bj][m][n][3] *= c3;
.LBB0_626:
	v_mov_b32_e32 v126, v158
	v_mov_b32_e32 v127, v159
	s_and_b64 vcc, exec, s[36:37]
	s_mov_b64 s[12:13], -1
	s_waitcnt vmcnt(0)
	v_lshlrev_b32_e32 v146, 16, v126
	v_and_b32_e32 v147, 0xffff0000, v126
	v_lshlrev_b32_e32 v142, 16, v127
	v_and_b32_e32 v143, 0xffff0000, v127
	s_cbranch_vccnz .LBB0_628
	v_mov_b32_e32 v126, v160
	v_mov_b32_e32 v127, v161
	s_waitcnt vmcnt(0)
	v_lshlrev_b32_e32 v1, 16, v126
	v_and_b32_e32 v126, 0xffff0000, v126
	v_max_f32_e32 v126, v126, v126
	v_lshlrev_b32_e32 v128, 16, v127
	v_and_b32_e32 v127, 0xffff0000, v127
	v_max_f32_e32 v126, 0xda24260, v126
	v_max_f32_e32 v127, v127, v127
	v_max_f32_e32 v129, 0xda24260, v127
	v_div_scale_f32 v127, s[12:13], v126, v126, v147
	v_rcp_f32_e32 v137, v127
	v_max_f32_e32 v1, v1, v1
	v_max_f32_e32 v1, 0xda24260, v1
	v_max_f32_e32 v128, v128, v128
	v_fma_f32 v144, -v127, v137, 1.0
	v_fmac_f32_e32 v137, v144, v137
	v_div_scale_f32 v144, vcc, v147, v126, v147
	v_mul_f32_e32 v148, v144, v137
	v_fma_f32 v149, -v127, v148, v144
	v_fmac_f32_e32 v148, v149, v137
	v_fma_f32 v127, -v127, v148, v144
	v_div_fmas_f32 v127, v127, v137, v148
	v_div_fixup_f32 v127, v127, v126, v147
	v_div_scale_f32 v126, s[12:13], v1, v1, v146
	v_rcp_f32_e32 v137, v126
	v_max_f32_e32 v128, 0xda24260, v128
	v_fma_f32 v144, -v126, v137, 1.0
	v_fmac_f32_e32 v137, v144, v137
	v_div_scale_f32 v144, vcc, v146, v1, v146
	v_mul_f32_e32 v148, v144, v137
	v_fma_f32 v149, -v126, v148, v144
	v_fmac_f32_e32 v148, v149, v137
	v_fma_f32 v126, -v126, v148, v144
	v_div_fmas_f32 v126, v126, v137, v148
	v_div_fixup_f32 v126, v126, v1, v146
	v_div_scale_f32 v1, s[12:13], v129, v129, v143
	v_rcp_f32_e32 v137, v1
	v_pk_mul_f32 v[126:127], v[118:119], v[126:127]
	v_fma_f32 v144, -v1, v137, 1.0
	v_fmac_f32_e32 v137, v144, v137
	v_div_scale_f32 v144, vcc, v143, v129, v143
	v_mul_f32_e32 v148, v144, v137
	v_fma_f32 v149, -v1, v148, v144
	v_fmac_f32_e32 v148, v149, v137
	v_fma_f32 v1, -v1, v148, v144
	v_div_fmas_f32 v1, v1, v137, v148
	v_div_fixup_f32 v129, v1, v129, v143
	v_div_scale_f32 v1, s[12:13], v128, v128, v142
	v_rcp_f32_e32 v137, v1
	s_mov_b64 s[12:13], 0
	v_fma_f32 v144, -v1, v137, 1.0
	v_fmac_f32_e32 v137, v144, v137
	v_div_scale_f32 v144, vcc, v142, v128, v142
	v_mul_f32_e32 v148, v144, v137
	v_fma_f32 v149, -v1, v148, v144
	v_fmac_f32_e32 v148, v149, v137
	v_fma_f32 v1, -v1, v148, v144
	v_div_fmas_f32 v1, v1, v137, v148
	v_div_fixup_f32 v128, v1, v128, v142
	v_pk_mul_f32 v[128:129], v[120:121], v[128:129]

; __device__ __forceinline__ float lo_bf(unsigned u) { return __uint_as_float(u << 16); }
; __device__ __forceinline__ float hi_bf(unsigned u) { return __uint_as_float(u & 0xffff0000u); }
; __device__ __forceinline__ void phase_merge(const Ctx& a, LAS unsigned char* lds) {
;     ...
;                             const bf16_t* gp = g + (size_t)row * NG + col;
;                             u32x2 gc = *(const u32x2*)(gp + seg * DM);
;                             float c0 = lo_bf(gc[0]), c1 = hi_bf(gc[0]), c2 = lo_bf(gc[1]), c3 = hi_bf(gc[1]);
;                             if (seg < 2) {
;                                 u32x2 gn = *(const u32x2*)(gp + (seg + 1) * DM);
;                                 c0 = c0 / fmaxf(lo_bf(gn[0]), 1e-30f); c1 = c1 / fmaxf(hi_bf(gn[0]), 1e-30f);
;                                 c2 = c2 / fmaxf(lo_bf(gn[1]), 1e-30f); c3 = c3 / fmaxf(hi_bf(gn[1]), 1e-30f);
;                                 acc[ai][bj][m][n][0] *= c0; acc[ai][bj][m][n][1] *= c1; acc[ai][bj][m][n][2] *= c2; acc[ai][bj][m][n][3] *= c3;
.LBB0_630:
	v_mov_b32_e32 v118, v162
	v_mov_b32_e32 v119, v163
	s_and_b64 vcc, exec, s[36:37]
	s_mov_b64 s[12:13], -1
	s_waitcnt vmcnt(0)
	v_lshlrev_b32_e32 v146, 16, v118
	v_and_b32_e32 v147, 0xffff0000, v118
	v_lshlrev_b32_e32 v142, 16, v119
	v_and_b32_e32 v143, 0xffff0000, v119
	s_cbranch_vccnz .LBB0_632
	v_mov_b32_e32 v118, v164
	v_mov_b32_e32 v119, v165
	s_waitcnt vmcnt(0)
	v_lshlrev_b32_e32 v1, 16, v118
	v_and_b32_e32 v118, 0xffff0000, v118
	v_max_f32_e32 v118, v118, v118
	v_lshlrev_b32_e32 v120, 16, v119
	v_and_b32_e32 v119, 0xffff0000, v119
	v_max_f32_e32 v118, 0xda24260, v118
	v_max_f32_e32 v119, v119, v119
	v_max_f32_e32 v121, 0xda24260, v119
	v_div_scale_f32 v119, s[12:13], v118, v118, v147
	v_rcp_f32_e32 v137, v119
	v_max_f32_e32 v1, v1, v1
	v_max_f32_e32 v1, 0xda24260, v1
	v_max_f32_e32 v120, v120, v120
	v_fma_f32 v144, -v119, v137, 1.0
	v_fmac_f32_e32 v137, v144, v137
	v_div_scale_f32 v144, vcc, v147, v118, v147
	v_mul_f32_e32 v148, v144, v137
	v_fma_f32 v149, -v119, v148, v144
	v_fmac_f32_e32 v148, v149, v137
	v_fma_f32 v119, -v119, v148, v144
	v_div_fmas_f32 v119, v119, v137, v148
	v_div_fixup_f32 v119, v119, v118, v147
	v_div_scale_f32 v118, s[12:13], v1, v1, v146
	v_rcp_f32_e32 v137, v118
	v_max_f32_e32 v120, 0xda24260, v120
	v_fma_f32 v144, -v118, v137, 1.0
	v_fmac_f32_e32 v137, v144, v137
	v_div_scale_f32 v144, vcc, v146, v1, v146
	v_mul_f32_e32 v148, v144, v137
	v_fma_f32 v149, -v118, v148, v144
	v_fmac_f32_e32 v148, v149, v137
	v_fma_f32 v118, -v118, v148, v144
	v_div_fmas_f32 v118, v118, v137, v148
	v_div_fixup_f32 v118, v118, v1, v146
	v_div_scale_f32 v1, s[12:13], v121, v121, v143
	v_rcp_f32_e32 v137, v1
	v_pk_mul_f32 v[118:119], v[110:111], v[118:119]
	v_fma_f32 v144, -v1, v137, 1.0
	v_fmac_f32_e32 v137, v144, v137
	v_div_scale_f32 v144, vcc, v143, v121, v143
	v_mul_f32_e32 v148, v144, v137
	v_fma_f32 v149, -v1, v148, v144
	v_fmac_f32_e32 v148, v149, v137
	v_fma_f32 v1, -v1, v148, v144
	v_div_fmas_f32 v1, v1, v137, v148
	v_div_fixup_f32 v121, v1, v121, v143
	v_div_scale_f32 v1, s[12:13], v120, v120, v142
	v_rcp_f32_e32 v137, v1
	s_mov_b64 s[12:13], 0
	v_fma_f32 v144, -v1, v137, 1.0
	v_fmac_f32_e32 v137, v144, v137
	v_div_scale_f32 v144, vcc, v142, v120, v142
	v_mul_f32_e32 v148, v144, v137
	v_fma_f32 v149, -v1, v148, v144
	v_fmac_f32_e32 v148, v149, v137
	v_fma_f32 v1, -v1, v148, v144
	v_div_fmas_f32 v1, v1, v137, v148
	v_div_fixup_f32 v120, v1, v120, v142
	v_pk_mul_f32 v[120:121], v[112:113], v[120:121]

; __device__ __forceinline__ float lo_bf(unsigned u) { return __uint_as_float(u << 16); }
; __device__ __forceinline__ float hi_bf(unsigned u) { return __uint_as_float(u & 0xffff0000u); }
; __device__ __forceinline__ void phase_merge(const Ctx& a, LAS unsigned char* lds) {
;     ...
;                             const bf16_t* gp = g + (size_t)row * NG + col;
;                             u32x2 gc = *(const u32x2*)(gp + seg * DM);
;                             float c0 = lo_bf(gc[0]), c1 = hi_bf(gc[0]), c2 = lo_bf(gc[1]), c3 = hi_bf(gc[1]);
;                             if (seg < 2) {
;                                 u32x2 gn = *(const u32x2*)(gp + (seg + 1) * DM);
;                                 c0 = c0 / fmaxf(lo_bf(gn[0]), 1e-30f); c1 = c1 / fmaxf(hi_bf(gn[0]), 1e-30f);
;                                 c2 = c2 / fmaxf(lo_bf(gn[1]), 1e-30f); c3 = c3 / fmaxf(hi_bf(gn[1]), 1e-30f);
;                                 acc[ai][bj][m][n][0] *= c0; acc[ai][bj][m][n][1] *= c1; acc[ai][bj][m][n][2] *= c2; acc[ai][bj][m][n][3] *= c3;
.LBB0_634:
	v_mov_b32_e32 v110, v166
	v_mov_b32_e32 v111, v167
	s_and_b64 vcc, exec, s[36:37]
	s_mov_b64 s[12:13], -1
	s_waitcnt vmcnt(0)
	v_lshlrev_b32_e32 v146, 16, v110
	v_and_b32_e32 v147, 0xffff0000, v110
	v_lshlrev_b32_e32 v142, 16, v111
	v_and_b32_e32 v143, 0xffff0000, v111
	s_cbranch_vccnz .LBB0_636
	v_mov_b32_e32 v110, v168
	v_mov_b32_e32 v111, v169
	s_waitcnt vmcnt(0)
	v_lshlrev_b32_e32 v1, 16, v110
	v_and_b32_e32 v110, 0xffff0000, v110
	v_max_f32_e32 v110, v110, v110
	v_lshlrev_b32_e32 v112, 16, v111
	v_and_b32_e32 v111, 0xffff0000, v111
	v_max_f32_e32 v110, 0xda24260, v110
	v_max_f32_e32 v111, v111, v111
	v_max_f32_e32 v113, 0xda24260, v111
	v_div_scale_f32 v111, s[12:13], v110, v110, v147
	v_rcp_f32_e32 v137, v111
	v_max_f32_e32 v1, v1, v1
	v_max_f32_e32 v1, 0xda24260, v1
	v_max_f32_e32 v112, v112, v112
	v_fma_f32 v138, -v111, v137, 1.0
	v_fmac_f32_e32 v137, v138, v137
	v_div_scale_f32 v138, vcc, v147, v110, v147
	v_mul_f32_e32 v139, v138, v137
	v_fma_f32 v144, -v111, v139, v138
	v_fmac_f32_e32 v139, v144, v137
	v_fma_f32 v111, -v111, v139, v138
	v_div_fmas_f32 v111, v111, v137, v139
	v_div_fixup_f32 v111, v111, v110, v147
	v_div_scale_f32 v110, s[12:13], v1, v1, v146
	v_rcp_f32_e32 v137, v110
	v_max_f32_e32 v112, 0xda24260, v112
	v_fma_f32 v138, -v110, v137, 1.0
	v_fmac_f32_e32 v137, v138, v137
	v_div_scale_f32 v138, vcc, v146, v1, v146
	v_mul_f32_e32 v139, v138, v137
	v_fma_f32 v144, -v110, v139, v138
	v_fmac_f32_e32 v139, v144, v137
	v_fma_f32 v110, -v110, v139, v138
	v_div_fmas_f32 v110, v110, v137, v139
	v_div_fixup_f32 v110, v110, v1, v146
	v_div_scale_f32 v1, s[12:13], v113, v113, v143
	v_rcp_f32_e32 v137, v1
	v_pk_mul_f32 v[110:111], v[102:103], v[110:111]
	v_fma_f32 v138, -v1, v137, 1.0
	v_fmac_f32_e32 v137, v138, v137
	v_div_scale_f32 v138, vcc, v143, v113, v143
	v_mul_f32_e32 v139, v138, v137
	v_fma_f32 v144, -v1, v139, v138
	v_fmac_f32_e32 v139, v144, v137
	v_fma_f32 v1, -v1, v139, v138
	v_div_fmas_f32 v1, v1, v137, v139
	v_div_fixup_f32 v113, v1, v113, v143
	v_div_scale_f32 v1, s[12:13], v112, v112, v142
	v_rcp_f32_e32 v137, v1
	s_mov_b64 s[12:13], 0
	v_fma_f32 v138, -v1, v137, 1.0
	v_fmac_f32_e32 v137, v138, v137
	v_div_scale_f32 v138, vcc, v142, v112, v142
	v_mul_f32_e32 v139, v138, v137
	v_fma_f32 v144, -v1, v139, v138
	v_fmac_f32_e32 v139, v144, v137
	v_fma_f32 v1, -v1, v139, v138
	v_div_fmas_f32 v1, v1, v137, v139
	v_div_fixup_f32 v112, v1, v112, v142
	v_pk_mul_f32 v[112:113], v[104:105], v[112:113]

; __device__ __forceinline__ float lo_bf(unsigned u) { return __uint_as_float(u << 16); }
; __device__ __forceinline__ float hi_bf(unsigned u) { return __uint_as_float(u & 0xffff0000u); }
; __device__ __forceinline__ void phase_merge(const Ctx& a, LAS unsigned char* lds) {
;     ...
;                     int row = pm * 256 + ai * 128 + t.wr * 64 + m * 16 + t.fr;
; #pragma unroll
;                     for (int bj = 0; bj < 2; ++bj)
; #pragma unroll
;                         for (int n = 0; n < 2; ++n) {
;                             int col = pn * 256 + bj * 128 + t.wc * 32 + n * 16 + t.fq * 4;
;                             const bf16_t* gp = g + (size_t)row * NG + col;
;                             u32x2 gc = *(const u32x2*)(gp + seg * DM);
;                             float c0 = lo_bf(gc[0]), c1 = hi_bf(gc[0]), c2 = lo_bf(gc[1]), c3 = hi_bf(gc[1]);
;                             if (seg < 2) {
;                                 u32x2 gn = *(const u32x2*)(gp + (seg + 1) * DM);
;                                 c0 = c0 / fmaxf(lo_bf(gn[0]), 1e-30f); c1 = c1 / fmaxf(hi_bf(gn[0]), 1e-30f);
;                                 c2 = c2 / fmaxf(lo_bf(gn[1]), 1e-30f); c3 = c3 / fmaxf(hi_bf(gn[1]), 1e-30f);
;                                 acc[ai][bj][m][n][0] *= c0; acc[ai][bj][m][n][1] *= c1; acc[ai][bj][m][n][2] *= c2; acc[ai][bj][m][n][3] *= c3;
.LBB0_638:
	v_add_u32_e32 v140, 0x90, v136
	v_mov_b64_e32 v[102:103], s[52:53]
	v_mad_i64_i32 v[102:103], s[12:13], v140, s84, v[102:103]
	v_lshl_add_u64 v[138:139], v[134:135], 1, v[102:103]
	v_mov_b32_e32 v102, v170
	v_mov_b32_e32 v103, v171
	s_and_b64 vcc, exec, s[36:37]
	s_mov_b64 s[12:13], -1
	s_waitcnt vmcnt(0)
	v_lshlrev_b32_e32 v146, 16, v102
	v_and_b32_e32 v147, 0xffff0000, v102
	v_lshlrev_b32_e32 v142, 16, v103
	v_and_b32_e32 v143, 0xffff0000, v103
	s_cbranch_vccnz .LBB0_640
	v_mov_b32_e32 v102, v172
	v_mov_b32_e32 v103, v173
	s_waitcnt vmcnt(0)
	v_lshlrev_b32_e32 v1, 16, v102
	v_and_b32_e32 v102, 0xffff0000, v102
	v_max_f32_e32 v102, v102, v102
	v_lshlrev_b32_e32 v104, 16, v103
	v_and_b32_e32 v103, 0xffff0000, v103
	v_max_f32_e32 v102, 0xda24260, v102
	v_max_f32_e32 v103, v103, v103
	v_max_f32_e32 v105, 0xda24260, v103
	v_div_scale_f32 v103, s[12:13], v102, v102, v147
	v_rcp_f32_e32 v137, v103
	v_max_f32_e32 v1, v1, v1
	v_max_f32_e32 v1, 0xda24260, v1
	v_max_f32_e32 v104, v104, v104
	v_fma_f32 v141, -v103, v137, 1.0
	v_fmac_f32_e32 v137, v141, v137
	v_div_scale_f32 v141, vcc, v147, v102, v147
	v_mul_f32_e32 v144, v141, v137
	v_fma_f32 v148, -v103, v144, v141
	v_fmac_f32_e32 v144, v148, v137
	v_fma_f32 v103, -v103, v144, v141
	v_div_fmas_f32 v103, v103, v137, v144
	v_div_fixup_f32 v103, v103, v102, v147
	v_div_scale_f32 v102, s[12:13], v1, v1, v146
	v_rcp_f32_e32 v137, v102
	v_max_f32_e32 v104, 0xda24260, v104
	v_fma_f32 v141, -v102, v137, 1.0
	v_fmac_f32_e32 v137, v141, v137
	v_div_scale_f32 v141, vcc, v146, v1, v146
	v_mul_f32_e32 v144, v141, v137
	v_fma_f32 v148, -v102, v144, v141
	v_fmac_f32_e32 v144, v148, v137
	v_fma_f32 v102, -v102, v144, v141
	v_div_fmas_f32 v102, v102, v137, v144
	v_div_fixup_f32 v102, v102, v1, v146
	v_div_scale_f32 v1, s[12:13], v105, v105, v143
	v_rcp_f32_e32 v137, v1
	v_pk_mul_f32 v[102:103], v[94:95], v[102:103]
	v_fma_f32 v141, -v1, v137, 1.0
	v_fmac_f32_e32 v137, v141, v137
	v_div_scale_f32 v141, vcc, v143, v105, v143
	v_mul_f32_e32 v144, v141, v137
	v_fma_f32 v148, -v1, v144, v141
	v_fmac_f32_e32 v144, v148, v137
	v_fma_f32 v1, -v1, v144, v141
	v_div_fmas_f32 v1, v1, v137, v144
	v_div_fixup_f32 v105, v1, v105, v143
	v_div_scale_f32 v1, s[12:13], v104, v104, v142
	v_rcp_f32_e32 v137, v1
	s_mov_b64 s[12:13], 0
	v_fma_f32 v141, -v1, v137, 1.0
	v_fmac_f32_e32 v137, v141, v137
	v_div_scale_f32 v141, vcc, v142, v104, v142
	v_mul_f32_e32 v144, v141, v137
	v_fma_f32 v148, -v1, v144, v141
	v_fmac_f32_e32 v144, v148, v137
	v_fma_f32 v1, -v1, v144, v141
	v_div_fmas_f32 v1, v1, v137, v144
	v_div_fixup_f32 v104, v1, v104, v142
	v_pk_mul_f32 v[104:105], v[96:97], v[104:105]

; __device__ __forceinline__ float lo_bf(unsigned u) { return __uint_as_float(u << 16); }
; __device__ __forceinline__ float hi_bf(unsigned u) { return __uint_as_float(u & 0xffff0000u); }
; __device__ __forceinline__ void phase_merge(const Ctx& a, LAS unsigned char* lds) {
;     ...
;                             const bf16_t* gp = g + (size_t)row * NG + col;
;                             u32x2 gc = *(const u32x2*)(gp + seg * DM);
;                             float c0 = lo_bf(gc[0]), c1 = hi_bf(gc[0]), c2 = lo_bf(gc[1]), c3 = hi_bf(gc[1]);
;                             if (seg < 2) {
;                                 u32x2 gn = *(const u32x2*)(gp + (seg + 1) * DM);
;                                 c0 = c0 / fmaxf(lo_bf(gn[0]), 1e-30f); c1 = c1 / fmaxf(hi_bf(gn[0]), 1e-30f);
;                                 c2 = c2 / fmaxf(lo_bf(gn[1]), 1e-30f); c3 = c3 / fmaxf(hi_bf(gn[1]), 1e-30f);
;                                 acc[ai][bj][m][n][0] *= c0; acc[ai][bj][m][n][1] *= c1; acc[ai][bj][m][n][2] *= c2; acc[ai][bj][m][n][3] *= c3;
.LBB0_642:
	v_mov_b32_e32 v94, v174
	v_mov_b32_e32 v95, v175
	s_and_b64 vcc, exec, s[36:37]
	s_mov_b64 s[12:13], -1
	s_waitcnt vmcnt(0)
	v_lshlrev_b32_e32 v146, 16, v94
	v_and_b32_e32 v147, 0xffff0000, v94
	v_lshlrev_b32_e32 v142, 16, v95
	v_and_b32_e32 v143, 0xffff0000, v95
	s_cbranch_vccnz .LBB0_644
	v_mov_b32_e32 v94, v176
	v_mov_b32_e32 v95, v177
	s_waitcnt vmcnt(0)
	v_lshlrev_b32_e32 v1, 16, v94
	v_and_b32_e32 v94, 0xffff0000, v94
	v_max_f32_e32 v94, v94, v94
	v_lshlrev_b32_e32 v96, 16, v95
	v_and_b32_e32 v95, 0xffff0000, v95
	v_max_f32_e32 v94, 0xda24260, v94
	v_max_f32_e32 v95, v95, v95
	v_max_f32_e32 v97, 0xda24260, v95
	v_div_scale_f32 v95, s[12:13], v94, v94, v147
	v_rcp_f32_e32 v137, v95
	v_max_f32_e32 v1, v1, v1
	v_max_f32_e32 v1, 0xda24260, v1
	v_max_f32_e32 v96, v96, v96
	v_fma_f32 v144, -v95, v137, 1.0
	v_fmac_f32_e32 v137, v144, v137
	v_div_scale_f32 v144, vcc, v147, v94, v147
	v_mul_f32_e32 v148, v144, v137
	v_fma_f32 v149, -v95, v148, v144
	v_fmac_f32_e32 v148, v149, v137
	v_fma_f32 v95, -v95, v148, v144
	v_div_fmas_f32 v95, v95, v137, v148
	v_div_fixup_f32 v95, v95, v94, v147
	v_div_scale_f32 v94, s[12:13], v1, v1, v146
	v_rcp_f32_e32 v137, v94
	v_max_f32_e32 v96, 0xda24260, v96
	v_fma_f32 v144, -v94, v137, 1.0
	v_fmac_f32_e32 v137, v144, v137
	v_div_scale_f32 v144, vcc, v146, v1, v146
	v_mul_f32_e32 v148, v144, v137
	v_fma_f32 v149, -v94, v148, v144
	v_fmac_f32_e32 v148, v149, v137
	v_fma_f32 v94, -v94, v148, v144
	v_div_fmas_f32 v94, v94, v137, v148
	v_div_fixup_f32 v94, v94, v1, v146
	v_div_scale_f32 v1, s[12:13], v97, v97, v143
	v_rcp_f32_e32 v137, v1
	v_pk_mul_f32 v[94:95], v[86:87], v[94:95]
	v_fma_f32 v144, -v1, v137, 1.0
	v_fmac_f32_e32 v137, v144, v137
	v_div_scale_f32 v144, vcc, v143, v97, v143
	v_mul_f32_e32 v148, v144, v137
	v_fma_f32 v149, -v1, v148, v144
	v_fmac_f32_e32 v148, v149, v137
	v_fma_f32 v1, -v1, v148, v144
	v_div_fmas_f32 v1, v1, v137, v148
	v_div_fixup_f32 v97, v1, v97, v143
	v_div_scale_f32 v1, s[12:13], v96, v96, v142
	v_rcp_f32_e32 v137, v1
	s_mov_b64 s[12:13], 0
	v_fma_f32 v144, -v1, v137, 1.0
	v_fmac_f32_e32 v137, v144, v137
	v_div_scale_f32 v144, vcc, v142, v96, v142
	v_mul_f32_e32 v148, v144, v137
	v_fma_f32 v149, -v1, v148, v144
	v_fmac_f32_e32 v148, v149, v137
	v_fma_f32 v1, -v1, v148, v144
	v_div_fmas_f32 v1, v1, v137, v148
	v_div_fixup_f32 v96, v1, v96, v142
	v_pk_mul_f32 v[96:97], v[88:89], v[96:97]

; __device__ __forceinline__ float lo_bf(unsigned u) { return __uint_as_float(u << 16); }
; __device__ __forceinline__ float hi_bf(unsigned u) { return __uint_as_float(u & 0xffff0000u); }
; __device__ __forceinline__ void phase_merge(const Ctx& a, LAS unsigned char* lds) {
;     ...
;                             const bf16_t* gp = g + (size_t)row * NG + col;
;                             u32x2 gc = *(const u32x2*)(gp + seg * DM);
;                             float c0 = lo_bf(gc[0]), c1 = hi_bf(gc[0]), c2 = lo_bf(gc[1]), c3 = hi_bf(gc[1]);
;                             if (seg < 2) {
;                                 u32x2 gn = *(const u32x2*)(gp + (seg + 1) * DM);
;                                 c0 = c0 / fmaxf(lo_bf(gn[0]), 1e-30f); c1 = c1 / fmaxf(hi_bf(gn[0]), 1e-30f);
;                                 c2 = c2 / fmaxf(lo_bf(gn[1]), 1e-30f); c3 = c3 / fmaxf(hi_bf(gn[1]), 1e-30f);
;                                 acc[ai][bj][m][n][0] *= c0; acc[ai][bj][m][n][1] *= c1; acc[ai][bj][m][n][2] *= c2; acc[ai][bj][m][n][3] *= c3;
.LBB0_646:
	v_mov_b32_e32 v86, v184
	v_mov_b32_e32 v87, v185
	s_and_b64 vcc, exec, s[36:37]
	s_mov_b64 s[12:13], -1
	s_waitcnt vmcnt(0)
	v_lshlrev_b32_e32 v146, 16, v86
	v_and_b32_e32 v147, 0xffff0000, v86
	v_lshlrev_b32_e32 v142, 16, v87
	v_and_b32_e32 v143, 0xffff0000, v87
	s_cbranch_vccnz .LBB0_648
	v_mov_b32_e32 v86, v186
	v_mov_b32_e32 v87, v187
	s_waitcnt vmcnt(0)
	v_lshlrev_b32_e32 v1, 16, v86
	v_and_b32_e32 v86, 0xffff0000, v86
	v_max_f32_e32 v86, v86, v86
	v_lshlrev_b32_e32 v88, 16, v87
	v_and_b32_e32 v87, 0xffff0000, v87
	v_max_f32_e32 v86, 0xda24260, v86
	v_max_f32_e32 v87, v87, v87
	v_max_f32_e32 v89, 0xda24260, v87
	v_div_scale_f32 v87, s[12:13], v86, v86, v147
	v_rcp_f32_e32 v137, v87
	v_max_f32_e32 v1, v1, v1
	v_max_f32_e32 v1, 0xda24260, v1
	v_max_f32_e32 v88, v88, v88
	v_fma_f32 v144, -v87, v137, 1.0
	v_fmac_f32_e32 v137, v144, v137
	v_div_scale_f32 v144, vcc, v147, v86, v147
	v_mul_f32_e32 v148, v144, v137
	v_fma_f32 v149, -v87, v148, v144
	v_fmac_f32_e32 v148, v149, v137
	v_fma_f32 v87, -v87, v148, v144
	v_div_fmas_f32 v87, v87, v137, v148
	v_div_fixup_f32 v87, v87, v86, v147
	v_div_scale_f32 v86, s[12:13], v1, v1, v146
	v_rcp_f32_e32 v137, v86
	v_max_f32_e32 v88, 0xda24260, v88
	v_fma_f32 v144, -v86, v137, 1.0
	v_fmac_f32_e32 v137, v144, v137
	v_div_scale_f32 v144, vcc, v146, v1, v146
	v_mul_f32_e32 v148, v144, v137
	v_fma_f32 v149, -v86, v148, v144
	v_fmac_f32_e32 v148, v149, v137
	v_fma_f32 v86, -v86, v148, v144
	v_div_fmas_f32 v86, v86, v137, v148
	v_div_fixup_f32 v86, v86, v1, v146
	v_div_scale_f32 v1, s[12:13], v89, v89, v143
	v_rcp_f32_e32 v137, v1
	v_pk_mul_f32 v[86:87], v[78:79], v[86:87]
	v_fma_f32 v144, -v1, v137, 1.0
	v_fmac_f32_e32 v137, v144, v137
	v_div_scale_f32 v144, vcc, v143, v89, v143
	v_mul_f32_e32 v148, v144, v137
	v_fma_f32 v149, -v1, v148, v144
	v_fmac_f32_e32 v148, v149, v137
	v_fma_f32 v1, -v1, v148, v144
	v_div_fmas_f32 v1, v1, v137, v148
	v_div_fixup_f32 v89, v1, v89, v143
	v_div_scale_f32 v1, s[12:13], v88, v88, v142
	v_rcp_f32_e32 v137, v1
	s_mov_b64 s[12:13], 0
	v_fma_f32 v144, -v1, v137, 1.0
	v_fmac_f32_e32 v137, v144, v137
	v_div_scale_f32 v144, vcc, v142, v88, v142
	v_mul_f32_e32 v148, v144, v137
	v_fma_f32 v149, -v1, v148, v144
	v_fmac_f32_e32 v148, v149, v137
	v_fma_f32 v1, -v1, v148, v144
	v_div_fmas_f32 v1, v1, v137, v148
	v_div_fixup_f32 v88, v1, v88, v142
	v_pk_mul_f32 v[88:89], v[80:81], v[88:89]

; __device__ __forceinline__ float lo_bf(unsigned u) { return __uint_as_float(u << 16); }
; __device__ __forceinline__ float hi_bf(unsigned u) { return __uint_as_float(u & 0xffff0000u); }
; __device__ __forceinline__ void phase_merge(const Ctx& a, LAS unsigned char* lds) {
;     ...
;                             const bf16_t* gp = g + (size_t)row * NG + col;
;                             u32x2 gc = *(const u32x2*)(gp + seg * DM);
;                             float c0 = lo_bf(gc[0]), c1 = hi_bf(gc[0]), c2 = lo_bf(gc[1]), c3 = hi_bf(gc[1]);
;                             if (seg < 2) {
;                                 u32x2 gn = *(const u32x2*)(gp + (seg + 1) * DM);
;                                 c0 = c0 / fmaxf(lo_bf(gn[0]), 1e-30f); c1 = c1 / fmaxf(hi_bf(gn[0]), 1e-30f);
;                                 c2 = c2 / fmaxf(lo_bf(gn[1]), 1e-30f); c3 = c3 / fmaxf(hi_bf(gn[1]), 1e-30f);
;                                 acc[ai][bj][m][n][0] *= c0; acc[ai][bj][m][n][1] *= c1; acc[ai][bj][m][n][2] *= c2; acc[ai][bj][m][n][3] *= c3;
.LBB0_650:
	v_mov_b32_e32 v78, v188
	v_mov_b32_e32 v79, v189
	s_and_b64 vcc, exec, s[36:37]
	s_mov_b64 s[12:13], -1
	s_waitcnt vmcnt(0)
	v_lshlrev_b32_e32 v146, 16, v78
	v_and_b32_e32 v147, 0xffff0000, v78
	v_lshlrev_b32_e32 v142, 16, v79
	v_and_b32_e32 v143, 0xffff0000, v79
	s_cbranch_vccnz .LBB0_652
	v_mov_b32_e32 v78, v190
	v_mov_b32_e32 v79, v191
	s_waitcnt vmcnt(0)
	v_lshlrev_b32_e32 v1, 16, v78
	v_and_b32_e32 v78, 0xffff0000, v78
	v_max_f32_e32 v78, v78, v78
	v_lshlrev_b32_e32 v80, 16, v79
	v_and_b32_e32 v79, 0xffff0000, v79
	v_max_f32_e32 v78, 0xda24260, v78
	v_max_f32_e32 v79, v79, v79
	v_max_f32_e32 v81, 0xda24260, v79
	v_div_scale_f32 v79, s[12:13], v78, v78, v147
	v_rcp_f32_e32 v137, v79
	v_max_f32_e32 v1, v1, v1
	v_max_f32_e32 v1, 0xda24260, v1
	v_max_f32_e32 v80, v80, v80
	v_fma_f32 v138, -v79, v137, 1.0
	v_fmac_f32_e32 v137, v138, v137
	v_div_scale_f32 v138, vcc, v147, v78, v147
	v_mul_f32_e32 v139, v138, v137
	v_fma_f32 v144, -v79, v139, v138
	v_fmac_f32_e32 v139, v144, v137
	v_fma_f32 v79, -v79, v139, v138
	v_div_fmas_f32 v79, v79, v137, v139
	v_div_fixup_f32 v79, v79, v78, v147
	v_div_scale_f32 v78, s[12:13], v1, v1, v146
	v_rcp_f32_e32 v137, v78
	v_max_f32_e32 v80, 0xda24260, v80
	v_fma_f32 v138, -v78, v137, 1.0
	v_fmac_f32_e32 v137, v138, v137
	v_div_scale_f32 v138, vcc, v146, v1, v146
	v_mul_f32_e32 v139, v138, v137
	v_fma_f32 v144, -v78, v139, v138
	v_fmac_f32_e32 v139, v144, v137
	v_fma_f32 v78, -v78, v139, v138
	v_div_fmas_f32 v78, v78, v137, v139
	v_div_fixup_f32 v78, v78, v1, v146
	v_div_scale_f32 v1, s[12:13], v81, v81, v143
	v_rcp_f32_e32 v137, v1
	v_pk_mul_f32 v[78:79], v[70:71], v[78:79]
	v_fma_f32 v138, -v1, v137, 1.0
	v_fmac_f32_e32 v137, v138, v137
	v_div_scale_f32 v138, vcc, v143, v81, v143
	v_mul_f32_e32 v139, v138, v137
	v_fma_f32 v144, -v1, v139, v138
	v_fmac_f32_e32 v139, v144, v137
	v_fma_f32 v1, -v1, v139, v138
	v_div_fmas_f32 v1, v1, v137, v139
	v_div_fixup_f32 v81, v1, v81, v143
	v_div_scale_f32 v1, s[12:13], v80, v80, v142
	v_rcp_f32_e32 v137, v1
	s_mov_b64 s[12:13], 0
	v_fma_f32 v138, -v1, v137, 1.0
	v_fmac_f32_e32 v137, v138, v137
	v_div_scale_f32 v138, vcc, v142, v80, v142
	v_mul_f32_e32 v139, v138, v137
	v_fma_f32 v144, -v1, v139, v138
	v_fmac_f32_e32 v139, v144, v137
	v_fma_f32 v1, -v1, v139, v138
	v_div_fmas_f32 v1, v1, v137, v139
	v_div_fixup_f32 v80, v1, v80, v142
	v_pk_mul_f32 v[80:81], v[72:73], v[80:81]

; __device__ __forceinline__ float lo_bf(unsigned u) { return __uint_as_float(u << 16); }
; __device__ __forceinline__ float hi_bf(unsigned u) { return __uint_as_float(u & 0xffff0000u); }
; __device__ __forceinline__ void phase_merge(const Ctx& a, LAS unsigned char* lds) {
;     ...
;                     int row = pm * 256 + ai * 128 + t.wr * 64 + m * 16 + t.fr;
; #pragma unroll
;                     for (int bj = 0; bj < 2; ++bj)
; #pragma unroll
;                         for (int n = 0; n < 2; ++n) {
;                             int col = pn * 256 + bj * 128 + t.wc * 32 + n * 16 + t.fq * 4;
;                             const bf16_t* gp = g + (size_t)row * NG + col;
;                             u32x2 gc = *(const u32x2*)(gp + seg * DM);
;                             float c0 = lo_bf(gc[0]), c1 = hi_bf(gc[0]), c2 = lo_bf(gc[1]), c3 = hi_bf(gc[1]);
;                             if (seg < 2) {
;                                 u32x2 gn = *(const u32x2*)(gp + (seg + 1) * DM);
;                                 c0 = c0 / fmaxf(lo_bf(gn[0]), 1e-30f); c1 = c1 / fmaxf(hi_bf(gn[0]), 1e-30f);
;                                 c2 = c2 / fmaxf(lo_bf(gn[1]), 1e-30f); c3 = c3 / fmaxf(hi_bf(gn[1]), 1e-30f);
;                                 acc[ai][bj][m][n][0] *= c0; acc[ai][bj][m][n][1] *= c1; acc[ai][bj][m][n][2] *= c2; acc[ai][bj][m][n][3] *= c3;
.LBB0_654:
	v_add_u32_e32 v140, 0xa0, v136
	v_mov_b64_e32 v[70:71], s[52:53]
	v_mad_i64_i32 v[70:71], s[12:13], v140, s84, v[70:71]
	v_lshl_add_u64 v[138:139], v[134:135], 1, v[70:71]
	v_mov_b32_e32 v70, v192
	v_mov_b32_e32 v71, v193
	s_and_b64 vcc, exec, s[36:37]
	s_mov_b64 s[12:13], -1
	s_waitcnt vmcnt(0)
	v_lshlrev_b32_e32 v146, 16, v70
	v_and_b32_e32 v147, 0xffff0000, v70
	v_lshlrev_b32_e32 v142, 16, v71
	v_and_b32_e32 v143, 0xffff0000, v71
	s_cbranch_vccnz .LBB0_656
	v_mov_b32_e32 v70, v200
	v_mov_b32_e32 v71, v201
	s_waitcnt vmcnt(0)
	v_lshlrev_b32_e32 v1, 16, v70
	v_and_b32_e32 v70, 0xffff0000, v70
	v_max_f32_e32 v70, v70, v70
	v_lshlrev_b32_e32 v72, 16, v71
	v_and_b32_e32 v71, 0xffff0000, v71
	v_max_f32_e32 v70, 0xda24260, v70
	v_max_f32_e32 v71, v71, v71
	v_max_f32_e32 v73, 0xda24260, v71
	v_div_scale_f32 v71, s[12:13], v70, v70, v147
	v_rcp_f32_e32 v137, v71
	v_max_f32_e32 v1, v1, v1
	v_max_f32_e32 v1, 0xda24260, v1
	v_max_f32_e32 v72, v72, v72
	v_fma_f32 v141, -v71, v137, 1.0
	v_fmac_f32_e32 v137, v141, v137
	v_div_scale_f32 v141, vcc, v147, v70, v147
	v_mul_f32_e32 v144, v141, v137
	v_fma_f32 v148, -v71, v144, v141
	v_fmac_f32_e32 v144, v148, v137
	v_fma_f32 v71, -v71, v144, v141
	v_div_fmas_f32 v71, v71, v137, v144
	v_div_fixup_f32 v71, v71, v70, v147
	v_div_scale_f32 v70, s[12:13], v1, v1, v146
	v_rcp_f32_e32 v137, v70
	v_max_f32_e32 v72, 0xda24260, v72
	v_fma_f32 v141, -v70, v137, 1.0
	v_fmac_f32_e32 v137, v141, v137
	v_div_scale_f32 v141, vcc, v146, v1, v146
	v_mul_f32_e32 v144, v141, v137
	v_fma_f32 v148, -v70, v144, v141
	v_fmac_f32_e32 v144, v148, v137
	v_fma_f32 v70, -v70, v144, v141
	v_div_fmas_f32 v70, v70, v137, v144
	v_div_fixup_f32 v70, v70, v1, v146
	v_div_scale_f32 v1, s[12:13], v73, v73, v143
	v_rcp_f32_e32 v137, v1
	v_pk_mul_f32 v[70:71], v[62:63], v[70:71]
	v_fma_f32 v141, -v1, v137, 1.0
	v_fmac_f32_e32 v137, v141, v137
	v_div_scale_f32 v141, vcc, v143, v73, v143
	v_mul_f32_e32 v144, v141, v137
	v_fma_f32 v148, -v1, v144, v141
	v_fmac_f32_e32 v144, v148, v137
	v_fma_f32 v1, -v1, v144, v141
	v_div_fmas_f32 v1, v1, v137, v144
	v_div_fixup_f32 v73, v1, v73, v143
	v_div_scale_f32 v1, s[12:13], v72, v72, v142
	v_rcp_f32_e32 v137, v1
	s_mov_b64 s[12:13], 0
	v_fma_f32 v141, -v1, v137, 1.0
	v_fmac_f32_e32 v137, v141, v137
	v_div_scale_f32 v141, vcc, v142, v72, v142
	v_mul_f32_e32 v144, v141, v137
	v_fma_f32 v148, -v1, v144, v141
	v_fmac_f32_e32 v144, v148, v137
	v_fma_f32 v1, -v1, v144, v141
	v_div_fmas_f32 v1, v1, v137, v144
	v_div_fixup_f32 v72, v1, v72, v142
	v_pk_mul_f32 v[72:73], v[64:65], v[72:73]

; __device__ __forceinline__ float lo_bf(unsigned u) { return __uint_as_float(u << 16); }
; __device__ __forceinline__ float hi_bf(unsigned u) { return __uint_as_float(u & 0xffff0000u); }
; __device__ __forceinline__ void phase_merge(const Ctx& a, LAS unsigned char* lds) {
;     ...
;                             const bf16_t* gp = g + (size_t)row * NG + col;
;                             u32x2 gc = *(const u32x2*)(gp + seg * DM);
;                             float c0 = lo_bf(gc[0]), c1 = hi_bf(gc[0]), c2 = lo_bf(gc[1]), c3 = hi_bf(gc[1]);
;                             if (seg < 2) {
;                                 u32x2 gn = *(const u32x2*)(gp + (seg + 1) * DM);
;                                 c0 = c0 / fmaxf(lo_bf(gn[0]), 1e-30f); c1 = c1 / fmaxf(hi_bf(gn[0]), 1e-30f);
;                                 c2 = c2 / fmaxf(lo_bf(gn[1]), 1e-30f); c3 = c3 / fmaxf(hi_bf(gn[1]), 1e-30f);
;                                 acc[ai][bj][m][n][0] *= c0; acc[ai][bj][m][n][1] *= c1; acc[ai][bj][m][n][2] *= c2; acc[ai][bj][m][n][3] *= c3;
.LBB0_658:
	v_mov_b32_e32 v62, v202
	v_mov_b32_e32 v63, v203
	s_and_b64 vcc, exec, s[36:37]
	s_mov_b64 s[12:13], -1
	s_waitcnt vmcnt(0)
	v_lshlrev_b32_e32 v146, 16, v62
	v_and_b32_e32 v147, 0xffff0000, v62
	v_lshlrev_b32_e32 v142, 16, v63
	v_and_b32_e32 v143, 0xffff0000, v63
	s_cbranch_vccnz .LBB0_660
	v_mov_b32_e32 v62, v204
	v_mov_b32_e32 v63, v205
	s_waitcnt vmcnt(0)
	v_lshlrev_b32_e32 v1, 16, v62
	v_and_b32_e32 v62, 0xffff0000, v62
	v_max_f32_e32 v62, v62, v62
	v_lshlrev_b32_e32 v64, 16, v63
	v_and_b32_e32 v63, 0xffff0000, v63
	v_max_f32_e32 v62, 0xda24260, v62
	v_max_f32_e32 v63, v63, v63
	v_max_f32_e32 v65, 0xda24260, v63
	v_div_scale_f32 v63, s[12:13], v62, v62, v147
	v_rcp_f32_e32 v137, v63
	v_max_f32_e32 v1, v1, v1
	v_max_f32_e32 v1, 0xda24260, v1
	v_max_f32_e32 v64, v64, v64
	v_fma_f32 v144, -v63, v137, 1.0
	v_fmac_f32_e32 v137, v144, v137
	v_div_scale_f32 v144, vcc, v147, v62, v147
	v_mul_f32_e32 v148, v144, v137
	v_fma_f32 v149, -v63, v148, v144
	v_fmac_f32_e32 v148, v149, v137
	v_fma_f32 v63, -v63, v148, v144
	v_div_fmas_f32 v63, v63, v137, v148
	v_div_fixup_f32 v63, v63, v62, v147
	v_div_scale_f32 v62, s[12:13], v1, v1, v146
	v_rcp_f32_e32 v137, v62
	v_max_f32_e32 v64, 0xda24260, v64
	v_fma_f32 v144, -v62, v137, 1.0
	v_fmac_f32_e32 v137, v144, v137
	v_div_scale_f32 v144, vcc, v146, v1, v146
	v_mul_f32_e32 v148, v144, v137
	v_fma_f32 v149, -v62, v148, v144
	v_fmac_f32_e32 v148, v149, v137
	v_fma_f32 v62, -v62, v148, v144
	v_div_fmas_f32 v62, v62, v137, v148
	v_div_fixup_f32 v62, v62, v1, v146
	v_div_scale_f32 v1, s[12:13], v65, v65, v143
	v_rcp_f32_e32 v137, v1
	v_pk_mul_f32 v[62:63], v[54:55], v[62:63]
	v_fma_f32 v144, -v1, v137, 1.0
	v_fmac_f32_e32 v137, v144, v137
	v_div_scale_f32 v144, vcc, v143, v65, v143
	v_mul_f32_e32 v148, v144, v137
	v_fma_f32 v149, -v1, v148, v144
	v_fmac_f32_e32 v148, v149, v137
	v_fma_f32 v1, -v1, v148, v144
	v_div_fmas_f32 v1, v1, v137, v148
	v_div_fixup_f32 v65, v1, v65, v143
	v_div_scale_f32 v1, s[12:13], v64, v64, v142
	v_rcp_f32_e32 v137, v1
	s_mov_b64 s[12:13], 0
	v_fma_f32 v144, -v1, v137, 1.0
	v_fmac_f32_e32 v137, v144, v137
	v_div_scale_f32 v144, vcc, v142, v64, v142
	v_mul_f32_e32 v148, v144, v137
	v_fma_f32 v149, -v1, v148, v144
	v_fmac_f32_e32 v148, v149, v137
	v_fma_f32 v1, -v1, v148, v144
	v_div_fmas_f32 v1, v1, v137, v148
	v_div_fixup_f32 v64, v1, v64, v142
	v_pk_mul_f32 v[64:65], v[56:57], v[64:65]

; __device__ __forceinline__ float lo_bf(unsigned u) { return __uint_as_float(u << 16); }
; __device__ __forceinline__ float hi_bf(unsigned u) { return __uint_as_float(u & 0xffff0000u); }
; __device__ __forceinline__ void phase_merge(const Ctx& a, LAS unsigned char* lds) {
;     ...
;                             const bf16_t* gp = g + (size_t)row * NG + col;
;                             u32x2 gc = *(const u32x2*)(gp + seg * DM);
;                             float c0 = lo_bf(gc[0]), c1 = hi_bf(gc[0]), c2 = lo_bf(gc[1]), c3 = hi_bf(gc[1]);
;                             if (seg < 2) {
;                                 u32x2 gn = *(const u32x2*)(gp + (seg + 1) * DM);
;                                 c0 = c0 / fmaxf(lo_bf(gn[0]), 1e-30f); c1 = c1 / fmaxf(hi_bf(gn[0]), 1e-30f);
;                                 c2 = c2 / fmaxf(lo_bf(gn[1]), 1e-30f); c3 = c3 / fmaxf(hi_bf(gn[1]), 1e-30f);
;                                 acc[ai][bj][m][n][0] *= c0; acc[ai][bj][m][n][1] *= c1; acc[ai][bj][m][n][2] *= c2; acc[ai][bj][m][n][3] *= c3;
.LBB0_662:
	v_mov_b32_e32 v54, v206
	v_mov_b32_e32 v55, v207
	s_and_b64 vcc, exec, s[36:37]
	s_mov_b64 s[12:13], -1
	s_waitcnt vmcnt(0)
	v_lshlrev_b32_e32 v146, 16, v54
	v_and_b32_e32 v147, 0xffff0000, v54
	v_lshlrev_b32_e32 v142, 16, v55
	v_and_b32_e32 v143, 0xffff0000, v55
	s_cbranch_vccnz .LBB0_664
	v_mov_b32_e32 v54, v208
	v_mov_b32_e32 v55, v209
	s_waitcnt vmcnt(0)
	v_lshlrev_b32_e32 v1, 16, v54
	v_and_b32_e32 v54, 0xffff0000, v54
	v_max_f32_e32 v54, v54, v54
	v_lshlrev_b32_e32 v56, 16, v55
	v_and_b32_e32 v55, 0xffff0000, v55
	v_max_f32_e32 v54, 0xda24260, v54
	v_max_f32_e32 v55, v55, v55
	v_max_f32_e32 v57, 0xda24260, v55
	v_div_scale_f32 v55, s[12:13], v54, v54, v147
	v_rcp_f32_e32 v137, v55
	v_max_f32_e32 v1, v1, v1
	v_max_f32_e32 v1, 0xda24260, v1
	v_max_f32_e32 v56, v56, v56
	v_fma_f32 v144, -v55, v137, 1.0
	v_fmac_f32_e32 v137, v144, v137
	v_div_scale_f32 v144, vcc, v147, v54, v147
	v_mul_f32_e32 v148, v144, v137
	v_fma_f32 v149, -v55, v148, v144
	v_fmac_f32_e32 v148, v149, v137
	v_fma_f32 v55, -v55, v148, v144
	v_div_fmas_f32 v55, v55, v137, v148
	v_div_fixup_f32 v55, v55, v54, v147
	v_div_scale_f32 v54, s[12:13], v1, v1, v146
	v_rcp_f32_e32 v137, v54
	v_max_f32_e32 v56, 0xda24260, v56
	v_fma_f32 v144, -v54, v137, 1.0
	v_fmac_f32_e32 v137, v144, v137
	v_div_scale_f32 v144, vcc, v146, v1, v146
	v_mul_f32_e32 v148, v144, v137
	v_fma_f32 v149, -v54, v148, v144
	v_fmac_f32_e32 v148, v149, v137
	v_fma_f32 v54, -v54, v148, v144
	v_div_fmas_f32 v54, v54, v137, v148
	v_div_fixup_f32 v54, v54, v1, v146
	v_div_scale_f32 v1, s[12:13], v57, v57, v143
	v_rcp_f32_e32 v137, v1
	v_pk_mul_f32 v[54:55], v[46:47], v[54:55]
	v_fma_f32 v144, -v1, v137, 1.0
	v_fmac_f32_e32 v137, v144, v137
	v_div_scale_f32 v144, vcc, v143, v57, v143
	v_mul_f32_e32 v148, v144, v137
	v_fma_f32 v149, -v1, v148, v144
	v_fmac_f32_e32 v148, v149, v137
	v_fma_f32 v1, -v1, v148, v144
	v_div_fmas_f32 v1, v1, v137, v148
	v_div_fixup_f32 v57, v1, v57, v143
	v_div_scale_f32 v1, s[12:13], v56, v56, v142
	v_rcp_f32_e32 v137, v1
	s_mov_b64 s[12:13], 0
	v_fma_f32 v144, -v1, v137, 1.0
	v_fmac_f32_e32 v137, v144, v137
	v_div_scale_f32 v144, vcc, v142, v56, v142
	v_mul_f32_e32 v148, v144, v137
	v_fma_f32 v149, -v1, v148, v144
	v_fmac_f32_e32 v148, v149, v137
	v_fma_f32 v1, -v1, v148, v144
	v_div_fmas_f32 v1, v1, v137, v148
	v_div_fixup_f32 v56, v1, v56, v142
	v_pk_mul_f32 v[56:57], v[48:49], v[56:57]

; __device__ __forceinline__ float lo_bf(unsigned u) { return __uint_as_float(u << 16); }
; __device__ __forceinline__ float hi_bf(unsigned u) { return __uint_as_float(u & 0xffff0000u); }
; __device__ __forceinline__ void phase_merge(const Ctx& a, LAS unsigned char* lds) {
;     ...
;                             const bf16_t* gp = g + (size_t)row * NG + col;
;                             u32x2 gc = *(const u32x2*)(gp + seg * DM);
;                             float c0 = lo_bf(gc[0]), c1 = hi_bf(gc[0]), c2 = lo_bf(gc[1]), c3 = hi_bf(gc[1]);
;                             if (seg < 2) {
;                                 u32x2 gn = *(const u32x2*)(gp + (seg + 1) * DM);
;                                 c0 = c0 / fmaxf(lo_bf(gn[0]), 1e-30f); c1 = c1 / fmaxf(hi_bf(gn[0]), 1e-30f);
;                                 c2 = c2 / fmaxf(lo_bf(gn[1]), 1e-30f); c3 = c3 / fmaxf(hi_bf(gn[1]), 1e-30f);
;                                 acc[ai][bj][m][n][0] *= c0; acc[ai][bj][m][n][1] *= c1; acc[ai][bj][m][n][2] *= c2; acc[ai][bj][m][n][3] *= c3;
.LBB0_666:
	v_mov_b32_e32 v46, v210
	v_mov_b32_e32 v47, v211
	s_and_b64 vcc, exec, s[36:37]
	s_mov_b64 s[12:13], -1
	s_waitcnt vmcnt(0)
	v_lshlrev_b32_e32 v146, 16, v46
	v_and_b32_e32 v147, 0xffff0000, v46
	v_lshlrev_b32_e32 v142, 16, v47
	v_and_b32_e32 v143, 0xffff0000, v47
	s_cbranch_vccnz .LBB0_668
	v_mov_b32_e32 v46, v212
	v_mov_b32_e32 v47, v213
	s_waitcnt vmcnt(0)
	v_lshlrev_b32_e32 v1, 16, v46
	v_and_b32_e32 v46, 0xffff0000, v46
	v_max_f32_e32 v46, v46, v46
	v_lshlrev_b32_e32 v48, 16, v47
	v_and_b32_e32 v47, 0xffff0000, v47
	v_max_f32_e32 v46, 0xda24260, v46
	v_max_f32_e32 v47, v47, v47
	v_max_f32_e32 v49, 0xda24260, v47
	v_div_scale_f32 v47, s[12:13], v46, v46, v147
	v_rcp_f32_e32 v137, v47
	v_max_f32_e32 v1, v1, v1
	v_max_f32_e32 v1, 0xda24260, v1
	v_max_f32_e32 v48, v48, v48
	v_fma_f32 v138, -v47, v137, 1.0
	v_fmac_f32_e32 v137, v138, v137
	v_div_scale_f32 v138, vcc, v147, v46, v147
	v_mul_f32_e32 v139, v138, v137
	v_fma_f32 v144, -v47, v139, v138
	v_fmac_f32_e32 v139, v144, v137
	v_fma_f32 v47, -v47, v139, v138
	v_div_fmas_f32 v47, v47, v137, v139
	v_div_fixup_f32 v47, v47, v46, v147
	v_div_scale_f32 v46, s[12:13], v1, v1, v146
	v_rcp_f32_e32 v137, v46
	v_max_f32_e32 v48, 0xda24260, v48
	v_fma_f32 v138, -v46, v137, 1.0
	v_fmac_f32_e32 v137, v138, v137
	v_div_scale_f32 v138, vcc, v146, v1, v146
	v_mul_f32_e32 v139, v138, v137
	v_fma_f32 v144, -v46, v139, v138
	v_fmac_f32_e32 v139, v144, v137
	v_fma_f32 v46, -v46, v139, v138
	v_div_fmas_f32 v46, v46, v137, v139
	v_div_fixup_f32 v46, v46, v1, v146
	v_div_scale_f32 v1, s[12:13], v49, v49, v143
	v_rcp_f32_e32 v137, v1
	v_pk_mul_f32 v[46:47], v[38:39], v[46:47]
	v_fma_f32 v138, -v1, v137, 1.0
	v_fmac_f32_e32 v137, v138, v137
	v_div_scale_f32 v138, vcc, v143, v49, v143
	v_mul_f32_e32 v139, v138, v137
	v_fma_f32 v144, -v1, v139, v138
	v_fmac_f32_e32 v139, v144, v137
	v_fma_f32 v1, -v1, v139, v138
	v_div_fmas_f32 v1, v1, v137, v139
	v_div_fixup_f32 v49, v1, v49, v143
	v_div_scale_f32 v1, s[12:13], v48, v48, v142
	v_rcp_f32_e32 v137, v1
	s_mov_b64 s[12:13], 0
	v_fma_f32 v138, -v1, v137, 1.0
	v_fmac_f32_e32 v137, v138, v137
	v_div_scale_f32 v138, vcc, v142, v48, v142
	v_mul_f32_e32 v139, v138, v137
	v_fma_f32 v144, -v1, v139, v138
	v_fmac_f32_e32 v139, v144, v137
	v_fma_f32 v1, -v1, v139, v138
	v_div_fmas_f32 v1, v1, v137, v139
	v_div_fixup_f32 v48, v1, v48, v142
	v_pk_mul_f32 v[48:49], v[40:41], v[48:49]

; __device__ __forceinline__ float lo_bf(unsigned u) { return __uint_as_float(u << 16); }
; __device__ __forceinline__ float hi_bf(unsigned u) { return __uint_as_float(u & 0xffff0000u); }
; __device__ __forceinline__ void phase_merge(const Ctx& a, LAS unsigned char* lds) {
;     ...
;                     int row = pm * 256 + ai * 128 + t.wr * 64 + m * 16 + t.fr;
; #pragma unroll
;                     for (int bj = 0; bj < 2; ++bj)
; #pragma unroll
;                         for (int n = 0; n < 2; ++n) {
;                             int col = pn * 256 + bj * 128 + t.wc * 32 + n * 16 + t.fq * 4;
;                             const bf16_t* gp = g + (size_t)row * NG + col;
;                             u32x2 gc = *(const u32x2*)(gp + seg * DM);
;                             float c0 = lo_bf(gc[0]), c1 = hi_bf(gc[0]), c2 = lo_bf(gc[1]), c3 = hi_bf(gc[1]);
;                             if (seg < 2) {
;                                 u32x2 gn = *(const u32x2*)(gp + (seg + 1) * DM);
;                                 c0 = c0 / fmaxf(lo_bf(gn[0]), 1e-30f); c1 = c1 / fmaxf(hi_bf(gn[0]), 1e-30f);
;                                 c2 = c2 / fmaxf(lo_bf(gn[1]), 1e-30f); c3 = c3 / fmaxf(hi_bf(gn[1]), 1e-30f);
;                                 acc[ai][bj][m][n][0] *= c0; acc[ai][bj][m][n][1] *= c1; acc[ai][bj][m][n][2] *= c2; acc[ai][bj][m][n][3] *= c3;
.LBB0_670:
	v_add_u32_e32 v138, 0xb0, v136
	v_mov_b64_e32 v[38:39], s[52:53]
	v_mad_i64_i32 v[38:39], s[12:13], v138, s84, v[38:39]
	v_lshl_add_u64 v[136:137], v[134:135], 1, v[38:39]
	v_mov_b32_e32 v38, v214
	v_mov_b32_e32 v39, v215
	s_and_b64 vcc, exec, s[36:37]
	s_mov_b64 s[12:13], -1
	s_waitcnt vmcnt(0)
	v_lshlrev_b32_e32 v142, 16, v38
	v_and_b32_e32 v143, 0xffff0000, v38
	v_lshlrev_b32_e32 v140, 16, v39
	v_and_b32_e32 v141, 0xffff0000, v39
	s_cbranch_vccnz .LBB0_672
	v_mov_b32_e32 v38, v216
	v_mov_b32_e32 v39, v217
	s_waitcnt vmcnt(0)
	v_lshlrev_b32_e32 v1, 16, v38
	v_and_b32_e32 v38, 0xffff0000, v38
	v_max_f32_e32 v38, v38, v38
	v_lshlrev_b32_e32 v40, 16, v39
	v_and_b32_e32 v39, 0xffff0000, v39
	v_max_f32_e32 v38, 0xda24260, v38
	v_max_f32_e32 v39, v39, v39
	v_max_f32_e32 v41, 0xda24260, v39
	v_div_scale_f32 v39, s[12:13], v38, v38, v143
	v_rcp_f32_e32 v139, v39
	v_max_f32_e32 v1, v1, v1
	v_max_f32_e32 v1, 0xda24260, v1
	v_max_f32_e32 v40, v40, v40
	v_fma_f32 v144, -v39, v139, 1.0
	v_fmac_f32_e32 v139, v144, v139
	v_div_scale_f32 v144, vcc, v143, v38, v143
	v_mul_f32_e32 v146, v144, v139
	v_fma_f32 v147, -v39, v146, v144
	v_fmac_f32_e32 v146, v147, v139
	v_fma_f32 v39, -v39, v146, v144
	v_div_fmas_f32 v39, v39, v139, v146
	v_div_fixup_f32 v39, v39, v38, v143
	v_div_scale_f32 v38, s[12:13], v1, v1, v142
	v_rcp_f32_e32 v139, v38
	v_max_f32_e32 v40, 0xda24260, v40
	v_fma_f32 v144, -v38, v139, 1.0
	v_fmac_f32_e32 v139, v144, v139
	v_div_scale_f32 v144, vcc, v142, v1, v142
	v_mul_f32_e32 v146, v144, v139
	v_fma_f32 v147, -v38, v146, v144
	v_fmac_f32_e32 v146, v147, v139
	v_fma_f32 v38, -v38, v146, v144
	v_div_fmas_f32 v38, v38, v139, v146
	v_div_fixup_f32 v38, v38, v1, v142
	v_div_scale_f32 v1, s[12:13], v41, v41, v141
	v_rcp_f32_e32 v139, v1
	v_pk_mul_f32 v[38:39], v[30:31], v[38:39]
	v_fma_f32 v144, -v1, v139, 1.0
	v_fmac_f32_e32 v139, v144, v139
	v_div_scale_f32 v144, vcc, v141, v41, v141
	v_mul_f32_e32 v146, v144, v139
	v_fma_f32 v147, -v1, v146, v144
	v_fmac_f32_e32 v146, v147, v139
	v_fma_f32 v1, -v1, v146, v144
	v_div_fmas_f32 v1, v1, v139, v146
	v_div_fixup_f32 v41, v1, v41, v141
	v_div_scale_f32 v1, s[12:13], v40, v40, v140
	v_rcp_f32_e32 v139, v1
	s_mov_b64 s[12:13], 0
	v_fma_f32 v144, -v1, v139, 1.0
	v_fmac_f32_e32 v139, v144, v139
	v_div_scale_f32 v144, vcc, v140, v40, v140
	v_mul_f32_e32 v146, v144, v139
	v_fma_f32 v147, -v1, v146, v144
	v_fmac_f32_e32 v146, v147, v139
	v_fma_f32 v1, -v1, v146, v144
	v_div_fmas_f32 v1, v1, v139, v146
	v_div_fixup_f32 v40, v1, v40, v140
	v_pk_mul_f32 v[40:41], v[32:33], v[40:41]

; __device__ __forceinline__ float lo_bf(unsigned u) { return __uint_as_float(u << 16); }
; __device__ __forceinline__ float hi_bf(unsigned u) { return __uint_as_float(u & 0xffff0000u); }
; __device__ __forceinline__ void phase_merge(const Ctx& a, LAS unsigned char* lds) {
;     ...
;                             const bf16_t* gp = g + (size_t)row * NG + col;
;                             u32x2 gc = *(const u32x2*)(gp + seg * DM);
;                             float c0 = lo_bf(gc[0]), c1 = hi_bf(gc[0]), c2 = lo_bf(gc[1]), c3 = hi_bf(gc[1]);
;                             if (seg < 2) {
;                                 u32x2 gn = *(const u32x2*)(gp + (seg + 1) * DM);
;                                 c0 = c0 / fmaxf(lo_bf(gn[0]), 1e-30f); c1 = c1 / fmaxf(hi_bf(gn[0]), 1e-30f);
;                                 c2 = c2 / fmaxf(lo_bf(gn[1]), 1e-30f); c3 = c3 / fmaxf(hi_bf(gn[1]), 1e-30f);
;                                 acc[ai][bj][m][n][0] *= c0; acc[ai][bj][m][n][1] *= c1; acc[ai][bj][m][n][2] *= c2; acc[ai][bj][m][n][3] *= c3;
.LBB0_674:
	v_mov_b32_e32 v30, v218
	v_mov_b32_e32 v31, v219
	s_and_b64 vcc, exec, s[36:37]
	s_mov_b64 s[12:13], -1
	s_waitcnt vmcnt(0)
	v_lshlrev_b32_e32 v140, 16, v30
	v_and_b32_e32 v141, 0xffff0000, v30
	v_lshlrev_b32_e32 v138, 16, v31
	v_and_b32_e32 v139, 0xffff0000, v31
	s_cbranch_vccnz .LBB0_676
	v_mov_b32_e32 v30, v220
	v_mov_b32_e32 v31, v221
	s_waitcnt vmcnt(0)
	v_lshlrev_b32_e32 v1, 16, v30
	v_and_b32_e32 v30, 0xffff0000, v30
	v_max_f32_e32 v30, v30, v30
	v_lshlrev_b32_e32 v32, 16, v31
	v_and_b32_e32 v31, 0xffff0000, v31
	v_max_f32_e32 v30, 0xda24260, v30
	v_max_f32_e32 v31, v31, v31
	v_max_f32_e32 v33, 0xda24260, v31
	v_div_scale_f32 v31, s[12:13], v30, v30, v141
	v_rcp_f32_e32 v142, v31
	v_max_f32_e32 v1, v1, v1
	v_max_f32_e32 v1, 0xda24260, v1
	v_max_f32_e32 v32, v32, v32
	v_fma_f32 v143, -v31, v142, 1.0
	v_fmac_f32_e32 v142, v143, v142
	v_div_scale_f32 v143, vcc, v141, v30, v141
	v_mul_f32_e32 v144, v143, v142
	v_fma_f32 v146, -v31, v144, v143
	v_fmac_f32_e32 v144, v146, v142
	v_fma_f32 v31, -v31, v144, v143
	v_div_fmas_f32 v31, v31, v142, v144
	v_div_fixup_f32 v31, v31, v30, v141
	v_div_scale_f32 v30, s[12:13], v1, v1, v140
	v_rcp_f32_e32 v142, v30
	v_max_f32_e32 v32, 0xda24260, v32
	v_fma_f32 v143, -v30, v142, 1.0
	v_fmac_f32_e32 v142, v143, v142
	v_div_scale_f32 v143, vcc, v140, v1, v140
	v_mul_f32_e32 v144, v143, v142
	v_fma_f32 v146, -v30, v144, v143
	v_fmac_f32_e32 v144, v146, v142
	v_fma_f32 v30, -v30, v144, v143
	v_div_fmas_f32 v30, v30, v142, v144
	v_div_fixup_f32 v30, v30, v1, v140
	v_div_scale_f32 v1, s[12:13], v33, v33, v139
	v_rcp_f32_e32 v142, v1
	v_pk_mul_f32 v[30:31], v[22:23], v[30:31]
	v_fma_f32 v143, -v1, v142, 1.0
	v_fmac_f32_e32 v142, v143, v142
	v_div_scale_f32 v143, vcc, v139, v33, v139
	v_mul_f32_e32 v144, v143, v142
	v_fma_f32 v146, -v1, v144, v143
	v_fmac_f32_e32 v144, v146, v142
	v_fma_f32 v1, -v1, v144, v143
	v_div_fmas_f32 v1, v1, v142, v144
	v_div_fixup_f32 v33, v1, v33, v139
	v_div_scale_f32 v1, s[12:13], v32, v32, v138
	v_rcp_f32_e32 v142, v1
	s_mov_b64 s[12:13], 0
	v_fma_f32 v143, -v1, v142, 1.0
	v_fmac_f32_e32 v142, v143, v142
	v_div_scale_f32 v143, vcc, v138, v32, v138
	v_mul_f32_e32 v144, v143, v142
	v_fma_f32 v146, -v1, v144, v143
	v_fmac_f32_e32 v144, v146, v142
	v_fma_f32 v1, -v1, v144, v143
	v_div_fmas_f32 v1, v1, v142, v144
	v_div_fixup_f32 v32, v1, v32, v138
	v_pk_mul_f32 v[32:33], v[24:25], v[32:33]

; __device__ __forceinline__ float lo_bf(unsigned u) { return __uint_as_float(u << 16); }
; __device__ __forceinline__ float hi_bf(unsigned u) { return __uint_as_float(u & 0xffff0000u); }
; __device__ __forceinline__ void phase_merge(const Ctx& a, LAS unsigned char* lds) {
;     ...
;                             const bf16_t* gp = g + (size_t)row * NG + col;
;                             u32x2 gc = *(const u32x2*)(gp + seg * DM);
;                             float c0 = lo_bf(gc[0]), c1 = hi_bf(gc[0]), c2 = lo_bf(gc[1]), c3 = hi_bf(gc[1]);
;                             if (seg < 2) {
;                                 u32x2 gn = *(const u32x2*)(gp + (seg + 1) * DM);
;                                 c0 = c0 / fmaxf(lo_bf(gn[0]), 1e-30f); c1 = c1 / fmaxf(hi_bf(gn[0]), 1e-30f);
;                                 c2 = c2 / fmaxf(lo_bf(gn[1]), 1e-30f); c3 = c3 / fmaxf(hi_bf(gn[1]), 1e-30f);
;                                 acc[ai][bj][m][n][0] *= c0; acc[ai][bj][m][n][1] *= c1; acc[ai][bj][m][n][2] *= c2; acc[ai][bj][m][n][3] *= c3;
.LBB0_678:
	v_mov_b32_e32 v22, v222
	v_mov_b32_e32 v23, v223
	s_and_b64 vcc, exec, s[36:37]
	s_mov_b64 s[12:13], -1
	s_waitcnt vmcnt(0)
	v_lshlrev_b32_e32 v140, 16, v22
	v_and_b32_e32 v141, 0xffff0000, v22
	v_lshlrev_b32_e32 v138, 16, v23
	v_and_b32_e32 v139, 0xffff0000, v23
	s_cbranch_vccnz .LBB0_680
	v_mov_b32_e32 v22, v224
	v_mov_b32_e32 v23, v225
	s_waitcnt vmcnt(0)
	v_lshlrev_b32_e32 v1, 16, v22
	v_and_b32_e32 v22, 0xffff0000, v22
	v_max_f32_e32 v22, v22, v22
	v_lshlrev_b32_e32 v24, 16, v23
	v_and_b32_e32 v23, 0xffff0000, v23
	v_max_f32_e32 v22, 0xda24260, v22
	v_max_f32_e32 v23, v23, v23
	v_max_f32_e32 v25, 0xda24260, v23
	v_div_scale_f32 v23, s[12:13], v22, v22, v141
	v_rcp_f32_e32 v142, v23
	v_max_f32_e32 v1, v1, v1
	v_max_f32_e32 v1, 0xda24260, v1
	v_max_f32_e32 v24, v24, v24
	v_fma_f32 v143, -v23, v142, 1.0
	v_fmac_f32_e32 v142, v143, v142
	v_div_scale_f32 v143, vcc, v141, v22, v141
	v_mul_f32_e32 v144, v143, v142
	v_fma_f32 v146, -v23, v144, v143
	v_fmac_f32_e32 v144, v146, v142
	v_fma_f32 v23, -v23, v144, v143
	v_div_fmas_f32 v23, v23, v142, v144
	v_div_fixup_f32 v23, v23, v22, v141
	v_div_scale_f32 v22, s[12:13], v1, v1, v140
	v_rcp_f32_e32 v142, v22
	v_max_f32_e32 v24, 0xda24260, v24
	v_fma_f32 v143, -v22, v142, 1.0
	v_fmac_f32_e32 v142, v143, v142
	v_div_scale_f32 v143, vcc, v140, v1, v140
	v_mul_f32_e32 v144, v143, v142
	v_fma_f32 v146, -v22, v144, v143
	v_fmac_f32_e32 v144, v146, v142
	v_fma_f32 v22, -v22, v144, v143
	v_div_fmas_f32 v22, v22, v142, v144
	v_div_fixup_f32 v22, v22, v1, v140
	v_div_scale_f32 v1, s[12:13], v25, v25, v139
	v_rcp_f32_e32 v142, v1
	v_pk_mul_f32 v[22:23], v[14:15], v[22:23]
	v_fma_f32 v143, -v1, v142, 1.0
	v_fmac_f32_e32 v142, v143, v142
	v_div_scale_f32 v143, vcc, v139, v25, v139
	v_mul_f32_e32 v144, v143, v142
	v_fma_f32 v146, -v1, v144, v143
	v_fmac_f32_e32 v144, v146, v142
	v_fma_f32 v1, -v1, v144, v143
	v_div_fmas_f32 v1, v1, v142, v144
	v_div_fixup_f32 v25, v1, v25, v139
	v_div_scale_f32 v1, s[12:13], v24, v24, v138
	v_rcp_f32_e32 v142, v1
	s_mov_b64 s[12:13], 0
	v_fma_f32 v143, -v1, v142, 1.0
	v_fmac_f32_e32 v142, v143, v142
	v_div_scale_f32 v143, vcc, v138, v24, v138
	v_mul_f32_e32 v144, v143, v142
	v_fma_f32 v146, -v1, v144, v143
	v_fmac_f32_e32 v144, v146, v142
	v_fma_f32 v1, -v1, v144, v143
	v_div_fmas_f32 v1, v1, v142, v144
	v_div_fixup_f32 v24, v1, v24, v138
	v_pk_mul_f32 v[24:25], v[16:17], v[24:25]

; __device__ __forceinline__ float lo_bf(unsigned u) { return __uint_as_float(u << 16); }
; __device__ __forceinline__ float hi_bf(unsigned u) { return __uint_as_float(u & 0xffff0000u); }
; __device__ __forceinline__ void phase_merge(const Ctx& a, LAS unsigned char* lds) {
;     ...
;                             const bf16_t* gp = g + (size_t)row * NG + col;
;                             u32x2 gc = *(const u32x2*)(gp + seg * DM);
;                             float c0 = lo_bf(gc[0]), c1 = hi_bf(gc[0]), c2 = lo_bf(gc[1]), c3 = hi_bf(gc[1]);
;                             if (seg < 2) {
;                                 u32x2 gn = *(const u32x2*)(gp + (seg + 1) * DM);
;                                 c0 = c0 / fmaxf(lo_bf(gn[0]), 1e-30f); c1 = c1 / fmaxf(hi_bf(gn[0]), 1e-30f);
;                                 c2 = c2 / fmaxf(lo_bf(gn[1]), 1e-30f); c3 = c3 / fmaxf(hi_bf(gn[1]), 1e-30f);
;                                 acc[ai][bj][m][n][0] *= c0; acc[ai][bj][m][n][1] *= c1; acc[ai][bj][m][n][2] *= c2; acc[ai][bj][m][n][3] *= c3;
.LBB0_682:
	v_mov_b32_e32 v14, v226
	v_mov_b32_e32 v15, v227
	s_and_b64 vcc, exec, s[36:37]
	s_mov_b64 s[12:13], -1
	s_waitcnt vmcnt(0)
	v_lshlrev_b32_e32 v140, 16, v14
	v_and_b32_e32 v141, 0xffff0000, v14
	v_lshlrev_b32_e32 v138, 16, v15
	v_and_b32_e32 v139, 0xffff0000, v15
	s_cbranch_vccnz .LBB0_684
	v_mov_b32_e32 v14, v228
	v_mov_b32_e32 v15, v229
	s_waitcnt vmcnt(0)
	v_lshlrev_b32_e32 v1, 16, v14
	v_and_b32_e32 v14, 0xffff0000, v14
	v_max_f32_e32 v14, v14, v14
	v_lshlrev_b32_e32 v16, 16, v15
	v_and_b32_e32 v15, 0xffff0000, v15
	v_max_f32_e32 v14, 0xda24260, v14
	v_max_f32_e32 v15, v15, v15
	v_max_f32_e32 v17, 0xda24260, v15
	v_div_scale_f32 v15, s[12:13], v14, v14, v141
	v_rcp_f32_e32 v136, v15
	v_max_f32_e32 v1, v1, v1
	v_max_f32_e32 v1, 0xda24260, v1
	v_max_f32_e32 v16, v16, v16
	v_fma_f32 v137, -v15, v136, 1.0
	v_fmac_f32_e32 v136, v137, v136
	v_div_scale_f32 v137, vcc, v141, v14, v141
	v_mul_f32_e32 v142, v137, v136
	v_fma_f32 v143, -v15, v142, v137
	v_fmac_f32_e32 v142, v143, v136
	v_fma_f32 v15, -v15, v142, v137
	v_div_fmas_f32 v15, v15, v136, v142
	v_div_fixup_f32 v15, v15, v14, v141
	v_div_scale_f32 v14, s[12:13], v1, v1, v140
	v_rcp_f32_e32 v136, v14
	v_max_f32_e32 v16, 0xda24260, v16
	v_fma_f32 v137, -v14, v136, 1.0
	v_fmac_f32_e32 v136, v137, v136
	v_div_scale_f32 v137, vcc, v140, v1, v140
	v_mul_f32_e32 v142, v137, v136
	v_fma_f32 v143, -v14, v142, v137
	v_fmac_f32_e32 v142, v143, v136
	v_fma_f32 v14, -v14, v142, v137
	v_div_fmas_f32 v14, v14, v136, v142
	v_div_fixup_f32 v14, v14, v1, v140
	v_div_scale_f32 v1, s[12:13], v17, v17, v139
	v_rcp_f32_e32 v136, v1
	v_pk_mul_f32 v[14:15], v[6:7], v[14:15]
	v_fma_f32 v137, -v1, v136, 1.0
	v_fmac_f32_e32 v136, v137, v136
	v_div_scale_f32 v137, vcc, v139, v17, v139
	v_mul_f32_e32 v142, v137, v136
	v_fma_f32 v143, -v1, v142, v137
	v_fmac_f32_e32 v142, v143, v136
	v_fma_f32 v1, -v1, v142, v137
	v_div_fmas_f32 v1, v1, v136, v142
	v_div_fixup_f32 v17, v1, v17, v139
	v_div_scale_f32 v1, s[12:13], v16, v16, v138
	v_rcp_f32_e32 v136, v1
	s_mov_b64 s[12:13], 0
	v_fma_f32 v137, -v1, v136, 1.0
	v_fmac_f32_e32 v136, v137, v136
	v_div_scale_f32 v137, vcc, v138, v16, v138
	v_mul_f32_e32 v142, v137, v136
	v_fma_f32 v143, -v1, v142, v137
	v_fmac_f32_e32 v142, v143, v136
	v_fma_f32 v1, -v1, v142, v137
	v_div_fmas_f32 v1, v1, v136, v142
	v_div_fixup_f32 v16, v1, v16, v138
	v_pk_mul_f32 v[16:17], v[8:9], v[16:17]
